# P9: token rows permuted at LDS-DMA time so each lane holds 4 consecutive tokens; conv epilogue rewritten with register-local taps (one DPP shift per boundary)
# speedup vs baseline: 1.0035x; 1.0008x over previous
;     __device__ __forceinline__ bool next(int i, Unit& u) const { return decode(i * G + c, u); }
; #define PG8_STAGE(bufoff, gbase, voff) do { _Pragma("unroll") for (int _i = 0; _i < 2; ++_i) \
;         __builtin_amdgcn_global_load_lds((const unsigned*)((const char*)(gbase) + (voff)[_i]), (LAS unsigned*)(lds + (bufoff) + ldsw + _i * 8192), 16, 0, 0); } while (0)
; #define PG8_WAIT_V(n) asm volatile("s_waitcnt vmcnt(" #n ")" ::: "memory")
; #define PG8_BAR __builtin_amdgcn_s_barrier()
; template <class Epi, class Sched, bool DEFER>
; __device__ __forceinline__ void gemm_fast_core(LAS unsigned char* lds, const GemmP g, const Sched& S, const Epi& E, f32x4 (&acc)[2][2][4][2], Unit& cur) {
;     ...
;     const int wid = __builtin_amdgcn_readfirstlane(tid >> 6), lane = tid & 63, wr = wid >> 2, wc = wid & 3, fr = lane & 15, fq = lane >> 4;
;     const int K = g.K, nt = K / BK;
;     unsigned voffA[2], voffB[2];
; #pragma unroll
;     for (int i = 0; i < 2; ++i) { int R, C; stage_rc(tid * 16 + i * 8192, R, C); voffA[i] = (unsigned)(R * g.lda + C) * 2u; voffB[i] = (unsigned)(R * g.ldb + C) * 2u; }
;     const size_t kstep = (size_t)(BK * 2);
;     const size_t hstepA = (size_t)HALF * g.lda * 2, hstepB = (size_t)HALF * g.ldb * 2;
;     const unsigned ldsw = (unsigned)wid * 1024u;
;     const int aoff = lds_byte(wr * 64 + fr, fq * 8), boff = lds_byte(wc * 32 + fr, fq * 8);
;     ...
;     Unit nxt; int ui = 0;
;     if (!S.next(0, cur)) return;
; #pragma unroll
;     for (int a = 0; a < 2; ++a)
; #pragma unroll
;         for (int b = 0; b < 2; ++b)
; #pragma unroll
;             for (int m = 0; m < 4; ++m)
; #pragma unroll
;                 for (int n = 0; n < 2; ++n) acc[a][b][m][n] = (f32x4){0.f, 0.f, 0.f, 0.f};
;     bf16x8 At[4][2], B0[2][2], B1[2][2];
;     const char* cA = (const char*)g.aptr(cur); const char* cB = (const char*)g.bptr(cur);
;     PG8_STAGE(PG8_SB(0, 0), cB, voffB); PG8_STAGE(PG8_SB(0, 1), cB + hstepB, voffB); PG8_STAGE(PG8_SA(0, 0), cA, voffA); PG8_STAGE(PG8_SA(0, 1), cA + hstepA, voffA);
;     if (wr == 1) PG8_BAR;
;     PG8_WAIT_V(2); PG8_BAR;
;     PG8_STAGE(PG8_SB(1, 0), cB + kstep, voffB); PG8_STAGE(PG8_SA(1, 0), cA + kstep, voffA); PG8_STAGE(PG8_SB(1, 1), cB + hstepB + kstep, voffB);
;     PG8_WAIT_V(6); PG8_BAR;
.LBB0_1790:
	s_or_b64 exec, exec, s[0:1]
	s_add_u32 s0, s66, 0x10100000
	s_addc_u32 s1, s67, 0
	v_mov_b32_e32 v11, v189
	s_waitcnt lgkmcnt(0)
	s_barrier
	s_cmpk_gt_i32 s88, 0x57f
	v_readfirstlane_b32 s5, v11
	s_cbranch_scc1 .LBB0_1806
	v_lshlrev_b32_e32 v0, 4, v11
	v_add_u32_e32 v1, 0x2000, v0
	v_ashrrev_i32_e32 v2, 31, v1
	v_lshrrev_b32_e32 v2, 22, v2
	v_add_u32_e32 v2, v1, v2
	v_ashrrev_i32_e32 v8, 10, v2
	v_mul_i32_i24_e32 v3, 0x400, v8
	v_sub_u32_e32 v1, v1, v3
	s_ashr_i32 s2, s88, 31
	v_lshrrev_b32_e32 v3, 4, v1
	s_lshr_b32 s2, s2, 29
	v_bitop3_b32 v1, v3, v1, 32 bitop3:0x6c
	s_add_i32 s2, s88, s2
	s_ashr_i32 s7, s5, 6
	v_ashrrev_i32_e32 v3, 31, v1
	s_ashr_i32 s3, s2, 3
	s_and_b32 s2, s2, -8
	s_ashr_i32 s6, s5, 8
	s_lshl_b32 s36, s7, 10
	v_lshrrev_b32_e32 v3, 26, v3
	s_sub_i32 s2, s88, s2
	v_add_u32_e32 v3, v1, v3
	s_cmp_lt_i32 s2, 0
	s_movk_i32 s37, 0xb1
	v_ashrrev_i32_e32 v9, 6, v3
	v_and_b32_e32 v3, 0xc0, v3
	s_cselect_b32 s4, s37, 0xb0
	v_sub_u32_e32 v1, v1, v3
	v_mov_b32_e32 v3, 1
	s_mul_i32 s2, s2, s4
	v_lshlrev_b32_e32 v2, 5, v8
	v_ashrrev_i16_sdwa v1, v3, sext(v1) dst_sel:DWORD dst_unused:UNUSED_PAD src0_sel:DWORD src1_sel:BYTE_0
	s_add_i32 s2, s2, s3
	v_and_b32_e32 v2, 32, v2
	v_bfe_i32 v10, v1, 0, 16
	s_mul_hi_i32 s3, s2, 0x2e8ba2e9
	v_add_u32_e32 v1, v2, v10
	v_lshlrev_b32_e32 v2, 3, v8
	s_lshr_b32 s4, s3, 31
	s_ashr_i32 s3, s3, 6
	v_and_b32_e32 v2, 0xffff0, v2
	s_add_i32 s3, s3, s4
	v_add_lshl_u32 v2, v9, v2, 12
	s_lshl_b32 s8, s3, 3
	s_mulk_i32 s3, 0x160
	v_lshl_add_u32 v160, v1, 1, v2
	v_bfe_i32 v2, v11, 27, 1
	s_sub_i32 s2, s2, s3
	v_lshrrev_b32_e32 v2, 22, v2
	s_sext_i32_i16 s3, s2
	v_add_u32_e32 v2, v0, v2
	s_bfe_u32 s3, s3, 0x3001c
	v_and_b32_e32 v2, 0xfffffc00, v2
	s_add_i32 s3, s2, s3
	v_sub_u32_e32 v0, v0, v2
	s_sext_i32_i16 s4, s3
	s_and_b32 s3, s3, 0xfff8
	v_lshrrev_b32_e32 v2, 4, v0
	s_sub_i32 s2, s2, s3
	v_bitop3_b32 v0, v2, v0, 32 bitop3:0x6c
	s_sext_i32_i16 s2, s2
	v_ashrrev_i32_e32 v2, 31, v0
	s_add_i32 s2, s8, s2
	v_ashrrev_i32_e32 v1, 31, v11
	v_lshrrev_b32_e32 v2, 26, v2
	s_ashr_i32 s3, s2, 31
	v_lshrrev_b32_e32 v1, 26, v1
	v_add_u32_e32 v2, v0, v2
	s_lshr_b32 s3, s3, 27
	v_add_u32_e32 v1, v11, v1
	v_ashrrev_i32_e32 v13, 6, v2
	v_and_b32_e32 v2, 0xc0, v2
	s_add_i32 s3, s2, s3
	v_ashrrev_i32_e32 v12, 6, v1
	v_sub_u32_e32 v0, v0, v2
	s_andn2_b32 s3, s3, 31
	v_lshlrev_b32_e32 v1, 5, v12
	v_ashrrev_i16_sdwa v0, v3, sext(v0) dst_sel:DWORD dst_unused:UNUSED_PAD src0_sel:DWORD src1_sel:BYTE_0
	s_lshr_b32 s4, s4, 3
	s_sub_i32 s26, s2, s3
	v_and_b32_e32 v1, 32, v1
	v_bfe_i32 v14, v0, 0, 16
	s_ashr_i32 s27, s26, 31
	s_bfe_i64 s[8:9], s[4:5], 0x100000
	v_add_u32_e32 v0, v1, v14
	v_lshlrev_b32_e32 v1, 3, v12
	s_lshl_b64 s[2:3], s[26:27], 20
	s_lshl_b64 s[8:9], s[8:9], 20
	v_and_b32_e32 v1, 0xffff0, v1
	s_add_u32 s30, s96, s8
	v_add_lshl_u32 v1, v13, v1, 12
	s_addc_u32 s31, s97, s9
	s_add_i32 s27, s36, 0
	v_lshl_add_u32 v162, v0, 1, v1
	s_add_i32 m0, s27, 0x10000
	v_mov_b32_e32 v163, 0
	v_and_b32_e32 v188, 63, v189
	v_lshrrev_b32_e32 v188, 2, v188
	v_mul_u32_u24_e32 v188, 3, v188
	v_bfe_u32 v194, v189, 7, 2
	v_mul_u32_u24_e32 v194, 15, v194
	v_sub_u32_e32 v188, v188, v194
	v_lshlrev_b32_e32 v188, 12, v188
	v_add_u32_e32 v190, v162, v188
	v_mov_b32_e32 v191, 0
	v_add_u32_e32 v192, v160, v188
	v_mov_b32_e32 v193, 0
	global_load_lds_dwordx4 v162, s[30:31]
	s_add_i32 m0, s27, 0x12000
	s_add_u32 s8, s30, 0x80000
	global_load_lds_dwordx4 v160, s[30:31]
	s_addc_u32 s9, s31, 0
	s_add_i32 m0, s27, 0x14000
	v_mov_b32_e32 v161, v163
	global_load_lds_dwordx4 v162, s[8:9]
	s_add_i32 m0, s27, 0x16000
	s_add_u32 s28, s90, s2
	s_addc_u32 s29, s91, s3
	s_add_i32 s38, s27, 0x2000
	global_load_lds_dwordx4 v160, s[8:9]
	s_mov_b32 m0, s27
	s_add_u32 s2, s28, 0x80000
	global_load_lds_dwordx4 v190, s[28:29]
	s_mov_b32 m0, s38
	s_addc_u32 s3, s29, 0
	s_add_i32 s39, s27, 0x4000
	global_load_lds_dwordx4 v192, s[28:29]
	s_mov_b32 m0, s39
	s_add_i32 s40, s27, 0x6000
	global_load_lds_dwordx4 v190, s[2:3]
	s_mov_b32 m0, s40
	s_cmp_eq_u32 s6, 1
	global_load_lds_dwordx4 v192, s[2:3]
	s_mov_b32 s41, 0
	v_lshl_add_u64 v[6:7], s[30:31], 0, v[162:163]
	v_lshl_add_u64 v[4:5], s[30:31], 0, v[160:161]
	v_lshl_add_u64 v[0:1], s[28:29], 0, v[190:191]
	s_cselect_b64 s[2:3], -1, 0
	s_cmp_lg_u32 s6, 1
	v_lshl_add_u64 v[2:3], s[28:29], 0, v[192:193]
	s_cbranch_scc1 .LBB0_1793
	s_barrier
.LBB0_1793:
	s_lshl_b32 s7, s7, 5
	s_mov_b64 s[8:9], 0x80
	s_and_b32 s16, s7, 0x60
	s_add_i32 m0, s27, 0x18000
	v_lshl_add_u64 v[6:7], v[6:7], 0, s[8:9]
	s_lshl_b32 s12, s6, 13
	s_lshl_b32 s7, s16, 7
	s_waitcnt vmcnt(2)
	s_barrier
	global_load_lds_dwordx4 v[6:7], off
	v_lshl_add_u64 v[4:5], v[4:5], 0, s[8:9]
	s_add_i32 m0, s27, 0x1a000
	s_add_i32 s42, s27, 0x8000
	s_add_i32 s43, s27, 0xa000
	global_load_lds_dwordx4 v[4:5], off
	v_lshl_add_u64 v[0:1], v[0:1], 0, s[8:9]
	s_mov_b32 m0, s42
	s_add_u32 s10, s30, 0x80080
	global_load_lds_dwordx4 v[0:1], off
	v_lshl_add_u64 v[0:1], v[2:3], 0, s[8:9]
	s_mov_b32 m0, s43
	s_addc_u32 s11, s31, 0
	global_load_lds_dwordx4 v[0:1], off
	s_add_i32 m0, s27, 0x1c000
	v_lshl_add_u64 v[0:1], s[10:11], 0, v[162:163]
	global_load_lds_dwordx4 v[0:1], off
	v_lshl_add_u64 v[0:1], s[10:11], 0, v[160:161]
	s_add_i32 m0, s27, 0x1e000
	v_lshlrev_b32_e32 v3, 2, v11
	global_load_lds_dwordx4 v[0:1], off
	v_bfe_u32 v1, v11, 4, 2
	v_and_b32_e32 v0, 15, v11
	v_lshlrev_b32_e32 v2, 4, v1
	v_lshl_or_b32 v2, v0, 6, v2
	v_and_b32_e32 v3, 32, v3
	s_sext_i32_i16 s33, s4
	v_lshl_or_b32 v195, s6, 6, v0
	v_bitop3_b32 v196, v2, s7, v3 bitop3:0xde
	s_cmpk_lt_u32 s5, 0x100
	v_cmp_eq_u32_e64 s[4:5], 15, v0
	v_cmp_eq_u32_e64 s[6:7], 0, v0
	v_lshlrev_b32_e32 v0, 15, v12
	v_and_b32_e32 v0, 0xffff0000, v0
	v_lshl_or_b32 v204, v1, 2, s16
	v_lshl_add_u32 v0, v13, 12, v0
	v_and_b32_e32 v1, 1, v12
	v_lshl_or_b32 v0, v1, 6, v0
	v_bitop3_b32 v4, v2, s12, v3 bitop3:0xde
	s_cselect_b64 s[10:11], -1, 0
	s_add_u32 s12, s56, 0xb000
	v_lshl_add_u32 v164, v14, 1, v0
	v_lshlrev_b32_e32 v0, 15, v8
	s_addc_u32 s13, s57, 0
	v_and_b32_e32 v0, 0xffff0000, v0
	s_waitcnt vmcnt(6)
	s_add_u32 s14, s56, 0x16000
	v_lshl_add_u32 v0, v9, 12, v0
	v_and_b32_e32 v1, 1, v8
	s_addc_u32 s15, s57, 0
	v_lshl_or_b32 v0, v1, 6, v0
	s_add_i32 s44, 0, 0x10000
	s_add_i32 s45, 0, 0x14000
	v_or_b32_e32 v197, 16, v195
	v_or_b32_e32 v198, 32, v195
	v_or_b32_e32 v199, 48, v195
	v_add_u32_e32 v200, 0x80, v195
	v_add_u32_e32 v201, 0x90, v195
	v_add_u32_e32 v202, 0xa0, v195
	v_add_u32_e32 v203, 0xb0, v195
	v_mov_b32_e32 v165, v163
	v_lshl_add_u32 v166, v10, 1, v0
	v_mov_b32_e32 v167, v163
	v_add_u32_e32 v164, v164, v188
	v_add_u32_e32 v166, v166, v188
	v_add_u32_e32 v205, s44, v196
	v_add_u32_e32 v206, s45, v196
	v_add_u32_e32 v207, 0, v4
	s_movk_i32 s46, 0x2c00
	s_barrier
	s_branch .LBB0_1796

; #define PG8_STAGE(bufoff, gbase, voff) do { _Pragma("unroll") for (int _i = 0; _i < 2; ++_i) \
;         __builtin_amdgcn_global_load_lds((const unsigned*)((const char*)(gbase) + (voff)[_i]), (LAS unsigned*)(lds + (bufoff) + ldsw + _i * 8192), 16, 0, 0); } while (0)
; #define PG8_LDA(dst, b, h) do { _Pragma("unroll") for (int m = 0; m < 4; ++m) _Pragma("unroll") for (int k = 0; k < 2; ++k) dst[m][k] = *(const LAS bf16x8*)(lds + PG8_SA(b, h) + aoff + m * 2048 + k * 1024); } while (0)
; #define PG8_LDB(dst, b, h) do { _Pragma("unroll") for (int n = 0; n < 2; ++n) _Pragma("unroll") for (int k = 0; k < 2; ++k) dst[n][k] = *(const LAS bf16x8*)(lds + PG8_SB(b, h) + boff + n * 2048 + k * 1024); } while (0)
; #define PG8_MMA(ai, bj, At, Bt) do { __builtin_amdgcn_s_setprio(1); _Pragma("unroll") for (int m = 0; m < 4; ++m) _Pragma("unroll") for (int n = 0; n < 2; ++n) _Pragma("unroll") for (int k = 0; k < 2; ++k) \
;         acc[ai][bj][m][n] = __builtin_amdgcn_mfma_f32_16x16x32_bf16(Bt[n][k], At[m][k], acc[ai][bj][m][n], 0, 0, 0); __builtin_amdgcn_s_setprio(0); } while (0)
; #define PG8_WAIT_V(n) asm volatile("s_waitcnt vmcnt(" #n ")" ::: "memory")
; #define PG8_WAIT_L(n) asm volatile("s_waitcnt lgkmcnt(" #n ")" ::: "memory")
; #define PG8_BAR __builtin_amdgcn_s_barrier()
; #define PG8_SCHED __builtin_amdgcn_sched_barrier(0)
; template <class Epi, class Sched, bool DEFER>
; __device__ __forceinline__ void gemm_fast_core(LAS unsigned char* lds, const GemmP g, const Sched& S, const Epi& E, f32x4 (&acc)[2][2][4][2], Unit& cur) {
;     ...
;             PG8_LDB(B0, 0, 0); PG8_LDB(B1, 0, 1); PG8_SCHED; PG8_LDA(At, 0, 0); PG8_STAGE(PG8_SA(1, 1), a1 + hstepA, voffA);
;             PG8_WAIT_V(8); PG8_WAIT_L(0); PG8_BAR; PG8_MMA(0, 0, At, B0); PG8_MMA(0, 1, At, B1); PG8_BAR; PG8_SCHED;
;             PG8_LDA(At, 0, 1); PG8_STAGE(PG8_SB(0, 0), b2, voffB); PG8_STAGE(PG8_SB(0, 1), b2 + hstepB, voffB); PG8_STAGE(PG8_SA(0, 0), a2, voffA);
;             PG8_WAIT_V(8); PG8_WAIT_L(0); PG8_BAR; PG8_MMA(1, 0, At, B0); PG8_MMA(1, 1, At, B1); PG8_BAR; PG8_SCHED;
.LBB0_1799:
	ds_read_b128 v[120:123], v205
	ds_read_b128 v[124:127], v205 offset:1024
	ds_read_b128 v[128:131], v205 offset:2048
	ds_read_b128 v[132:135], v205 offset:3072
	ds_read_b128 v[136:139], v206
	ds_read_b128 v[140:143], v206 offset:1024
	ds_read_b128 v[144:147], v206 offset:2048
	ds_read_b128 v[148:151], v206 offset:3072
	s_add_u32 s30, s28, 0xfff80080
	s_addc_u32 s31, s29, -1
	s_cmp_eq_u32 s51, 28
	s_cselect_b32 s35, s19, s31
	s_cselect_b32 s34, s47, s30
	s_cselect_b32 s31, s17, s50
	s_cselect_b32 s30, s48, s49
	v_lshl_add_u64 v[220:221], s[28:29], 0, v[164:165]
	s_add_i32 m0, s27, 0xc000
	ds_read_b128 v[168:171], v207
	ds_read_b128 v[172:175], v207 offset:1024
	ds_read_b128 v[176:179], v207 offset:2048
	ds_read_b128 v[180:183], v207 offset:3072
	ds_read_b128 v[184:187], v207 offset:4096
	ds_read_b128 v[208:211], v207 offset:5120
	ds_read_b128 v[212:215], v207 offset:6144
	ds_read_b128 v[216:219], v207 offset:7168
	global_load_lds_dwordx4 v[220:221], off
	v_lshl_add_u64 v[220:221], s[28:29], 0, v[166:167]
	s_add_i32 m0, s27, 0xe000
	s_nop 0
	global_load_lds_dwordx4 v[220:221], off
	s_waitcnt vmcnt(8)
	s_waitcnt lgkmcnt(0)
	s_barrier
	s_setprio 1
	s_waitcnt lgkmcnt(0)
	v_mfma_f32_16x16x32_bf16 v[156:159], v[120:123], v[168:171], v[156:159]
	v_mfma_f32_16x16x32_bf16 v[60:63], v[128:131], v[168:171], v[60:63]
	v_mfma_f32_16x16x32_bf16 v[116:119], v[120:123], v[176:179], v[116:119]
	v_mfma_f32_16x16x32_bf16 v[52:55], v[128:131], v[176:179], v[52:55]
	v_mfma_f32_16x16x32_bf16 v[108:111], v[120:123], v[184:187], v[108:111]
	v_mfma_f32_16x16x32_bf16 v[44:47], v[128:131], v[184:187], v[44:47]
	v_mfma_f32_16x16x32_bf16 v[100:103], v[120:123], v[212:215], v[100:103]
	v_mfma_f32_16x16x32_bf16 v[36:39], v[128:131], v[212:215], v[36:39]
	v_mfma_f32_16x16x32_bf16 v[156:159], v[124:127], v[172:175], v[156:159]
	v_mfma_f32_16x16x32_bf16 v[60:63], v[132:135], v[172:175], v[60:63]
	v_mfma_f32_16x16x32_bf16 v[116:119], v[124:127], v[180:183], v[116:119]
	v_mfma_f32_16x16x32_bf16 v[52:55], v[132:135], v[180:183], v[52:55]
	v_mfma_f32_16x16x32_bf16 v[108:111], v[124:127], v[208:211], v[108:111]
	v_mfma_f32_16x16x32_bf16 v[44:47], v[132:135], v[208:211], v[44:47]
	v_mfma_f32_16x16x32_bf16 v[100:103], v[124:127], v[216:219], v[100:103]
	v_mfma_f32_16x16x32_bf16 v[36:39], v[132:135], v[216:219], v[36:39]
	s_setprio 0
	s_setprio 1
	v_mfma_f32_16x16x32_bf16 v[152:155], v[136:139], v[168:171], v[152:155]
	v_mfma_f32_16x16x32_bf16 v[56:59], v[144:147], v[168:171], v[56:59]
	v_mfma_f32_16x16x32_bf16 v[112:115], v[136:139], v[176:179], v[112:115]
	v_mfma_f32_16x16x32_bf16 v[48:51], v[144:147], v[176:179], v[48:51]
	v_mfma_f32_16x16x32_bf16 v[104:107], v[136:139], v[184:187], v[104:107]
	v_mfma_f32_16x16x32_bf16 v[40:43], v[144:147], v[184:187], v[40:43]
	v_mfma_f32_16x16x32_bf16 v[96:99], v[136:139], v[212:215], v[96:99]
	v_mfma_f32_16x16x32_bf16 v[32:35], v[144:147], v[212:215], v[32:35]
	v_mfma_f32_16x16x32_bf16 v[152:155], v[140:143], v[172:175], v[152:155]
	v_mfma_f32_16x16x32_bf16 v[56:59], v[148:151], v[172:175], v[56:59]
	v_mfma_f32_16x16x32_bf16 v[112:115], v[140:143], v[180:183], v[112:115]
	v_mfma_f32_16x16x32_bf16 v[48:51], v[148:151], v[180:183], v[48:51]
	v_mfma_f32_16x16x32_bf16 v[104:107], v[140:143], v[208:211], v[104:107]
	v_mfma_f32_16x16x32_bf16 v[40:43], v[148:151], v[208:211], v[40:43]
	v_mfma_f32_16x16x32_bf16 v[96:99], v[140:143], v[216:219], v[96:99]
	v_mfma_f32_16x16x32_bf16 v[32:35], v[148:151], v[216:219], v[32:35]
	s_setprio 0
	s_barrier
	s_add_i32 s52, s44, s36
	v_lshl_add_u64 v[220:221], s[30:31], 0, v[162:163]
	s_mov_b32 m0, s52
	ds_read_b128 v[168:171], v207 offset:16384
	ds_read_b128 v[172:175], v207 offset:17408
	ds_read_b128 v[176:179], v207 offset:18432
	ds_read_b128 v[180:183], v207 offset:19456
	ds_read_b128 v[184:187], v207 offset:20480
	ds_read_b128 v[208:211], v207 offset:21504
	ds_read_b128 v[212:215], v207 offset:22528
	ds_read_b128 v[216:219], v207 offset:23552
	global_load_lds_dwordx4 v[220:221], off
	s_add_i32 m0, s52, 0x2000
	s_add_u32 s52, s30, 0x80000
	v_lshl_add_u64 v[222:223], s[30:31], 0, v[160:161]
	s_addc_u32 s53, s31, 0
	s_add_i32 s54, s45, s36
	global_load_lds_dwordx4 v[222:223], off
	v_lshl_add_u64 v[224:225], s[52:53], 0, v[162:163]
	s_mov_b32 m0, s54
	v_lshl_add_u64 v[226:227], s[34:35], 0, v[192:193]
	global_load_lds_dwordx4 v[224:225], off
	v_lshl_add_u64 v[224:225], s[52:53], 0, v[160:161]
	s_add_i32 m0, s54, 0x2000
	s_nop 0
	global_load_lds_dwordx4 v[224:225], off
	v_lshl_add_u64 v[224:225], s[34:35], 0, v[190:191]
	s_mov_b32 m0, s27
	s_nop 0
	global_load_lds_dwordx4 v[224:225], off
	s_mov_b32 m0, s38
	s_nop 0
	global_load_lds_dwordx4 v[226:227], off
	s_waitcnt vmcnt(8)
	s_waitcnt lgkmcnt(0)
	s_barrier
; #define PG8_STAGE(bufoff, gbase, voff) do { _Pragma("unroll") for (int _i = 0; _i < 2; ++_i) \
;         __builtin_amdgcn_global_load_lds((const unsigned*)((const char*)(gbase) + (voff)[_i]), (LAS unsigned*)(lds + (bufoff) + ldsw + _i * 8192), 16, 0, 0); } while (0)
; #define PG8_LDA(dst, b, h) do { _Pragma("unroll") for (int m = 0; m < 4; ++m) _Pragma("unroll") for (int k = 0; k < 2; ++k) dst[m][k] = *(const LAS bf16x8*)(lds + PG8_SA(b, h) + aoff + m * 2048 + k * 1024); } while (0)
; #define PG8_LDB(dst, b, h) do { _Pragma("unroll") for (int n = 0; n < 2; ++n) _Pragma("unroll") for (int k = 0; k < 2; ++k) dst[n][k] = *(const LAS bf16x8*)(lds + PG8_SB(b, h) + boff + n * 2048 + k * 1024); } while (0)
; #define PG8_MMA(ai, bj, At, Bt) do { __builtin_amdgcn_s_setprio(1); _Pragma("unroll") for (int m = 0; m < 4; ++m) _Pragma("unroll") for (int n = 0; n < 2; ++n) _Pragma("unroll") for (int k = 0; k < 2; ++k) \
;         acc[ai][bj][m][n] = __builtin_amdgcn_mfma_f32_16x16x32_bf16(Bt[n][k], At[m][k], acc[ai][bj][m][n], 0, 0, 0); __builtin_amdgcn_s_setprio(0); } while (0)
; #define PG8_WAIT_V(n) asm volatile("s_waitcnt vmcnt(" #n ")" ::: "memory")
; #define PG8_WAIT_L(n) asm volatile("s_waitcnt lgkmcnt(" #n ")" ::: "memory")
; #define PG8_BAR __builtin_amdgcn_s_barrier()
; #define PG8_SCHED __builtin_amdgcn_sched_barrier(0)
; template <class Epi, class Sched, bool DEFER>
; __device__ __forceinline__ void gemm_fast_core(LAS unsigned char* lds, const GemmP g, const Sched& S, const Epi& E, f32x4 (&acc)[2][2][4][2], Unit& cur) {
;     ...
;             PG8_WAIT_V(8); PG8_WAIT_L(0); PG8_BAR; PG8_MMA(1, 0, At, B0); PG8_MMA(1, 1, At, B1); PG8_BAR; PG8_SCHED;
;             PG8_LDB(B0, 1, 0); PG8_LDB(B1, 1, 1); PG8_SCHED; PG8_LDA(At, 1, 0); PG8_STAGE(PG8_SA(0, 1), a2 + hstepA, voffA);
;             PG8_WAIT_V(8); PG8_WAIT_L(0); PG8_BAR; PG8_MMA(0, 0, At, B0); PG8_MMA(0, 1, At, B1); PG8_BAR; PG8_SCHED;
;             PG8_LDA(At, 1, 1); PG8_STAGE(PG8_SB(1, 0), b3, voffB); PG8_STAGE(PG8_SB(1, 1), b3 + hstepB, voffB); PG8_STAGE(PG8_SA(1, 0), a3, voffA);
	s_setprio 1
	s_waitcnt lgkmcnt(0)
	v_mfma_f32_16x16x32_bf16 v[92:95], v[120:123], v[168:171], v[92:95]
	v_mfma_f32_16x16x32_bf16 v[28:31], v[128:131], v[168:171], v[28:31]
	v_mfma_f32_16x16x32_bf16 v[84:87], v[120:123], v[176:179], v[84:87]
	v_mfma_f32_16x16x32_bf16 v[20:23], v[128:131], v[176:179], v[20:23]
	v_mfma_f32_16x16x32_bf16 v[76:79], v[120:123], v[184:187], v[76:79]
	v_mfma_f32_16x16x32_bf16 v[12:15], v[128:131], v[184:187], v[12:15]
	v_mfma_f32_16x16x32_bf16 v[68:71], v[120:123], v[212:215], v[68:71]
	v_mfma_f32_16x16x32_bf16 v[4:7], v[128:131], v[212:215], v[4:7]
	v_mfma_f32_16x16x32_bf16 v[92:95], v[124:127], v[172:175], v[92:95]
	v_mfma_f32_16x16x32_bf16 v[28:31], v[132:135], v[172:175], v[28:31]
	v_mfma_f32_16x16x32_bf16 v[84:87], v[124:127], v[180:183], v[84:87]
	v_mfma_f32_16x16x32_bf16 v[20:23], v[132:135], v[180:183], v[20:23]
	v_mfma_f32_16x16x32_bf16 v[76:79], v[124:127], v[208:211], v[76:79]
	v_mfma_f32_16x16x32_bf16 v[12:15], v[132:135], v[208:211], v[12:15]
	v_mfma_f32_16x16x32_bf16 v[68:71], v[124:127], v[216:219], v[68:71]
	v_mfma_f32_16x16x32_bf16 v[4:7], v[132:135], v[216:219], v[4:7]
	s_setprio 0
	s_setprio 1
	v_mfma_f32_16x16x32_bf16 v[88:91], v[136:139], v[168:171], v[88:91]
	v_mfma_f32_16x16x32_bf16 v[24:27], v[144:147], v[168:171], v[24:27]
	v_mfma_f32_16x16x32_bf16 v[80:83], v[136:139], v[176:179], v[80:83]
	v_mfma_f32_16x16x32_bf16 v[16:19], v[144:147], v[176:179], v[16:19]
	v_mfma_f32_16x16x32_bf16 v[72:75], v[136:139], v[184:187], v[72:75]
	v_mfma_f32_16x16x32_bf16 v[8:11], v[144:147], v[184:187], v[8:11]
	v_mfma_f32_16x16x32_bf16 v[64:67], v[136:139], v[212:215], v[64:67]
	v_mfma_f32_16x16x32_bf16 v[0:3], v[144:147], v[212:215], v[0:3]
	v_mfma_f32_16x16x32_bf16 v[88:91], v[140:143], v[172:175], v[88:91]
	v_mfma_f32_16x16x32_bf16 v[24:27], v[148:151], v[172:175], v[24:27]
	v_mfma_f32_16x16x32_bf16 v[80:83], v[140:143], v[180:183], v[80:83]
	v_mfma_f32_16x16x32_bf16 v[16:19], v[148:151], v[180:183], v[16:19]
	v_mfma_f32_16x16x32_bf16 v[72:75], v[140:143], v[208:211], v[72:75]
	v_mfma_f32_16x16x32_bf16 v[8:11], v[148:151], v[208:211], v[8:11]
	v_mfma_f32_16x16x32_bf16 v[64:67], v[140:143], v[216:219], v[64:67]
	v_mfma_f32_16x16x32_bf16 v[0:3], v[148:151], v[216:219], v[0:3]
	s_setprio 0
	s_barrier
	s_add_i32 s52, 0, 0x18000
	s_add_i32 s53, 0, 0x1c000
	v_add_u32_e32 v132, s52, v196
	v_add_u32_e32 v148, s53, v196
	ds_read_b128 v[120:123], v132
	ds_read_b128 v[124:127], v132 offset:1024
	ds_read_b128 v[128:131], v132 offset:2048
	ds_read_b128 v[132:135], v132 offset:3072
	ds_read_b128 v[136:139], v148
	ds_read_b128 v[140:143], v148 offset:1024
	ds_read_b128 v[144:147], v148 offset:2048
	ds_read_b128 v[148:151], v148 offset:3072
	s_add_u32 s34, s34, 0x80000
	s_addc_u32 s35, s35, 0
	s_mov_b32 m0, s39
	v_lshl_add_u64 v[228:229], s[34:35], 0, v[190:191]
	ds_read_b128 v[168:171], v207 offset:32768
	ds_read_b128 v[172:175], v207 offset:33792
	ds_read_b128 v[176:179], v207 offset:34816
	ds_read_b128 v[180:183], v207 offset:35840
	ds_read_b128 v[184:187], v207 offset:36864
	ds_read_b128 v[208:211], v207 offset:37888
	ds_read_b128 v[212:215], v207 offset:38912
	ds_read_b128 v[216:219], v207 offset:39936
	global_load_lds_dwordx4 v[228:229], off
	v_lshl_add_u64 v[228:229], s[34:35], 0, v[192:193]
	s_mov_b32 m0, s40
	s_nop 0
	global_load_lds_dwordx4 v[228:229], off
	s_waitcnt vmcnt(8)
	s_waitcnt lgkmcnt(0)
	s_barrier
	s_setprio 1
	s_waitcnt lgkmcnt(0)
	v_mfma_f32_16x16x32_bf16 v[156:159], v[120:123], v[168:171], v[156:159]
	v_mfma_f32_16x16x32_bf16 v[60:63], v[128:131], v[168:171], v[60:63]
	v_mfma_f32_16x16x32_bf16 v[116:119], v[120:123], v[176:179], v[116:119]
	v_mfma_f32_16x16x32_bf16 v[52:55], v[128:131], v[176:179], v[52:55]
	v_mfma_f32_16x16x32_bf16 v[108:111], v[120:123], v[184:187], v[108:111]
	v_mfma_f32_16x16x32_bf16 v[44:47], v[128:131], v[184:187], v[44:47]
	v_mfma_f32_16x16x32_bf16 v[100:103], v[120:123], v[212:215], v[100:103]
	v_mfma_f32_16x16x32_bf16 v[36:39], v[128:131], v[212:215], v[36:39]
	v_mfma_f32_16x16x32_bf16 v[156:159], v[124:127], v[172:175], v[156:159]
	v_mfma_f32_16x16x32_bf16 v[60:63], v[132:135], v[172:175], v[60:63]
	v_mfma_f32_16x16x32_bf16 v[116:119], v[124:127], v[180:183], v[116:119]
	v_mfma_f32_16x16x32_bf16 v[52:55], v[132:135], v[180:183], v[52:55]
	v_mfma_f32_16x16x32_bf16 v[108:111], v[124:127], v[208:211], v[108:111]
	v_mfma_f32_16x16x32_bf16 v[44:47], v[132:135], v[208:211], v[44:47]
	v_mfma_f32_16x16x32_bf16 v[100:103], v[124:127], v[216:219], v[100:103]
	v_mfma_f32_16x16x32_bf16 v[36:39], v[132:135], v[216:219], v[36:39]
	s_setprio 0
	s_setprio 1
	v_mfma_f32_16x16x32_bf16 v[152:155], v[136:139], v[168:171], v[152:155]
	v_mfma_f32_16x16x32_bf16 v[56:59], v[144:147], v[168:171], v[56:59]
	v_mfma_f32_16x16x32_bf16 v[112:115], v[136:139], v[176:179], v[112:115]
	v_mfma_f32_16x16x32_bf16 v[48:51], v[144:147], v[176:179], v[48:51]
	v_mfma_f32_16x16x32_bf16 v[104:107], v[136:139], v[184:187], v[104:107]
	v_mfma_f32_16x16x32_bf16 v[40:43], v[144:147], v[184:187], v[40:43]
	v_mfma_f32_16x16x32_bf16 v[96:99], v[136:139], v[212:215], v[96:99]
	v_mfma_f32_16x16x32_bf16 v[32:35], v[144:147], v[212:215], v[32:35]
	v_mfma_f32_16x16x32_bf16 v[152:155], v[140:143], v[172:175], v[152:155]
	v_mfma_f32_16x16x32_bf16 v[56:59], v[148:151], v[172:175], v[56:59]
	v_mfma_f32_16x16x32_bf16 v[112:115], v[140:143], v[180:183], v[112:115]
	v_mfma_f32_16x16x32_bf16 v[48:51], v[148:151], v[180:183], v[48:51]
	v_mfma_f32_16x16x32_bf16 v[104:107], v[140:143], v[208:211], v[104:107]
	v_mfma_f32_16x16x32_bf16 v[40:43], v[148:151], v[208:211], v[40:43]
	v_mfma_f32_16x16x32_bf16 v[96:99], v[140:143], v[216:219], v[96:99]
	v_mfma_f32_16x16x32_bf16 v[32:35], v[148:151], v[216:219], v[32:35]
	s_setprio 0
	s_barrier
; #define PG8_STAGE(bufoff, gbase, voff) do { _Pragma("unroll") for (int _i = 0; _i < 2; ++_i) \
;         __builtin_amdgcn_global_load_lds((const unsigned*)((const char*)(gbase) + (voff)[_i]), (LAS unsigned*)(lds + (bufoff) + ldsw + _i * 8192), 16, 0, 0); } while (0)
; #define PG8_LDA(dst, b, h) do { _Pragma("unroll") for (int m = 0; m < 4; ++m) _Pragma("unroll") for (int k = 0; k < 2; ++k) dst[m][k] = *(const LAS bf16x8*)(lds + PG8_SA(b, h) + aoff + m * 2048 + k * 1024); } while (0)
; #define PG8_MMA(ai, bj, At, Bt) do { __builtin_amdgcn_s_setprio(1); _Pragma("unroll") for (int m = 0; m < 4; ++m) _Pragma("unroll") for (int n = 0; n < 2; ++n) _Pragma("unroll") for (int k = 0; k < 2; ++k) \
;         acc[ai][bj][m][n] = __builtin_amdgcn_mfma_f32_16x16x32_bf16(Bt[n][k], At[m][k], acc[ai][bj][m][n], 0, 0, 0); __builtin_amdgcn_s_setprio(0); } while (0)
; #define PG8_WAIT_V(n) asm volatile("s_waitcnt vmcnt(" #n ")" ::: "memory")
; #define PG8_WAIT_L(n) asm volatile("s_waitcnt lgkmcnt(" #n ")" ::: "memory")
; #define PG8_BAR __builtin_amdgcn_s_barrier()
; #define PG8_SCHED __builtin_amdgcn_sched_barrier(0)
;     __device__ __forceinline__ void tile(const f32x4 (&acc)[2][2][4][2], const Unit& u, int wr, int wc, int fr, int fq) const {
;     ...
;             const int cv = 128 * u.pn + 32 * wc + 16 * n + 4 * fq, cg = FF + cv;
;             const f32x4 wv0 = *(const f32x4*)(cw + cv), wv1 = *(const f32x4*)(cw + F2 + cv), wv2 = *(const f32x4*)(cw + 2 * F2 + cv), bv = *(const f32x4*)(cb + cv);
;             const f32x4 wg0 = *(const f32x4*)(cw + cg), wg1 = *(const f32x4*)(cw + F2 + cg), wg2 = *(const f32x4*)(cw + 2 * F2 + cg), bg = *(const f32x4*)(cb + cg);
; template <class Epi, class Sched, bool DEFER>
; __device__ __forceinline__ void gemm_fast_core(LAS unsigned char* lds, const GemmP g, const Sched& S, const Epi& E, f32x4 (&acc)[2][2][4][2], Unit& cur) {
;     ...
;             PG8_LDA(At, 1, 1); PG8_STAGE(PG8_SB(1, 0), b3, voffB); PG8_STAGE(PG8_SB(1, 1), b3 + hstepB, voffB); PG8_STAGE(PG8_SA(1, 0), a3, voffA);
;             PG8_WAIT_V(8); PG8_WAIT_L(0); PG8_BAR; PG8_MMA(1, 0, At, B0); PG8_MMA(1, 1, At, B1); PG8_BAR; PG8_SCHED;
;         }
	s_add_i32 s34, s52, s36
	v_lshl_add_u64 v[220:221], v[220:221], 0, s[8:9]
	s_mov_b32 m0, s34
	ds_read_b128 v[168:171], v207 offset:49152
	ds_read_b128 v[172:175], v207 offset:50176
	ds_read_b128 v[176:179], v207 offset:51200
	ds_read_b128 v[180:183], v207 offset:52224
	ds_read_b128 v[184:187], v207 offset:53248
	ds_read_b128 v[208:211], v207 offset:54272
	ds_read_b128 v[212:215], v207 offset:55296
	ds_read_b128 v[216:219], v207 offset:56320
	global_load_lds_dwordx4 v[220:221], off
	s_add_i32 m0, s34, 0x2000
	s_add_u32 s30, s30, 0x80080
	v_lshl_add_u64 v[220:221], v[222:223], 0, s[8:9]
	s_addc_u32 s31, s31, 0
	s_add_i32 s34, s53, s36
	global_load_lds_dwordx4 v[220:221], off
	v_lshl_add_u64 v[220:221], s[30:31], 0, v[162:163]
	s_mov_b32 m0, s34
	s_nop 0
	global_load_lds_dwordx4 v[220:221], off
	v_lshl_add_u64 v[220:221], s[30:31], 0, v[160:161]
	s_add_i32 m0, s34, 0x2000
	s_nop 0
	global_load_lds_dwordx4 v[220:221], off
	v_lshl_add_u64 v[220:221], v[224:225], 0, s[8:9]
	s_mov_b32 m0, s42
	s_nop 0
	global_load_lds_dwordx4 v[220:221], off
	v_lshl_add_u64 v[220:221], v[226:227], 0, s[8:9]
	s_mov_b32 m0, s43
	s_nop 0
	global_load_lds_dwordx4 v[220:221], off
	s_waitcnt vmcnt(8)
	s_waitcnt lgkmcnt(0)
	s_barrier
	s_setprio 1
	s_waitcnt lgkmcnt(0)
	v_mfma_f32_16x16x32_bf16 v[92:95], v[120:123], v[168:171], v[92:95]
	v_mfma_f32_16x16x32_bf16 v[28:31], v[128:131], v[168:171], v[28:31]
	v_mfma_f32_16x16x32_bf16 v[84:87], v[120:123], v[176:179], v[84:87]
	v_mfma_f32_16x16x32_bf16 v[20:23], v[128:131], v[176:179], v[20:23]
	v_mfma_f32_16x16x32_bf16 v[76:79], v[120:123], v[184:187], v[76:79]
	v_mfma_f32_16x16x32_bf16 v[12:15], v[128:131], v[184:187], v[12:15]
	v_mfma_f32_16x16x32_bf16 v[68:71], v[120:123], v[212:215], v[68:71]
	v_mfma_f32_16x16x32_bf16 v[4:7], v[128:131], v[212:215], v[4:7]
	v_mfma_f32_16x16x32_bf16 v[92:95], v[124:127], v[172:175], v[92:95]
	v_mfma_f32_16x16x32_bf16 v[28:31], v[132:135], v[172:175], v[28:31]
	v_mfma_f32_16x16x32_bf16 v[84:87], v[124:127], v[180:183], v[84:87]
	v_mfma_f32_16x16x32_bf16 v[20:23], v[132:135], v[180:183], v[20:23]
	v_mfma_f32_16x16x32_bf16 v[76:79], v[124:127], v[208:211], v[76:79]
	v_mfma_f32_16x16x32_bf16 v[12:15], v[132:135], v[208:211], v[12:15]
	v_mfma_f32_16x16x32_bf16 v[68:71], v[124:127], v[216:219], v[68:71]
	v_mfma_f32_16x16x32_bf16 v[4:7], v[132:135], v[216:219], v[4:7]
	s_setprio 0
	s_setprio 1
	v_mfma_f32_16x16x32_bf16 v[88:91], v[136:139], v[168:171], v[88:91]
	v_mfma_f32_16x16x32_bf16 v[24:27], v[144:147], v[168:171], v[24:27]
	v_mfma_f32_16x16x32_bf16 v[80:83], v[136:139], v[176:179], v[80:83]
	v_mfma_f32_16x16x32_bf16 v[16:19], v[144:147], v[176:179], v[16:19]
	v_mfma_f32_16x16x32_bf16 v[72:75], v[136:139], v[184:187], v[72:75]
	v_mfma_f32_16x16x32_bf16 v[8:11], v[144:147], v[184:187], v[8:11]
	v_mfma_f32_16x16x32_bf16 v[64:67], v[136:139], v[212:215], v[64:67]
	v_mfma_f32_16x16x32_bf16 v[0:3], v[144:147], v[212:215], v[0:3]
	v_mfma_f32_16x16x32_bf16 v[88:91], v[140:143], v[172:175], v[88:91]
	v_mfma_f32_16x16x32_bf16 v[24:27], v[148:151], v[172:175], v[24:27]
	v_mfma_f32_16x16x32_bf16 v[80:83], v[140:143], v[180:183], v[80:83]
	v_mfma_f32_16x16x32_bf16 v[16:19], v[148:151], v[180:183], v[16:19]
	v_mfma_f32_16x16x32_bf16 v[72:75], v[140:143], v[208:211], v[72:75]
	v_mfma_f32_16x16x32_bf16 v[8:11], v[148:151], v[208:211], v[8:11]
	v_mfma_f32_16x16x32_bf16 v[64:67], v[140:143], v[216:219], v[64:67]
	v_mfma_f32_16x16x32_bf16 v[0:3], v[148:151], v[216:219], v[0:3]
	s_setprio 0
	s_barrier
	s_add_i32 s51, s51, 2
	s_add_u32 s28, s28, 0x100
	s_addc_u32 s29, s29, 0
	s_add_u32 s49, s49, 0x100
	s_addc_u32 s50, s50, 0
	s_cmp_gt_u32 s51, 29
	s_cbranch_scc0 .LBB0_1799
	s_and_b64 vcc, exec, s[10:11]
	s_cbranch_vccz .LBB0_1802
	s_barrier
.LBB0_1802:
	v_lshl_or_b32 v170, s33, 7, v204
	v_lshlrev_b32_e32 v171, 2, v170
	v_add_u32_e32 v172, 0x5800, v171
	global_load_dwordx4 v[120:123], v171, s[56:57]
	global_load_dwordx4 v[124:127], v171, s[12:13]
	global_load_dwordx4 v[128:131], v171, s[14:15]
	global_load_dwordx4 v[132:135], v171, s[58:59]
	global_load_dwordx4 v[136:139], v172, s[56:57]
	global_load_dwordx4 v[140:143], v172, s[12:13]
	global_load_dwordx4 v[144:147], v172, s[14:15]
	global_load_dwordx4 v[148:151], v172, s[58:59]
	global_load_dwordx4 v[230:233], v171, s[56:57] offset:64
	global_load_dwordx4 v[234:237], v171, s[12:13] offset:64
	global_load_dwordx4 v[238:241], v171, s[14:15] offset:64
	global_load_dwordx4 v[242:245], v171, s[58:59] offset:64
	global_load_dwordx4 v[246:249], v172, s[56:57] offset:64
	global_load_dwordx4 v[250:253], v172, s[12:13] offset:64
	global_load_dwordx4 v[208:211], v172, s[14:15] offset:64
	global_load_dwordx4 v[212:215], v172, s[58:59] offset:64
	s_lshl_b32 s17, s26, 8
	v_and_b32_e32 v173, 64, v195
	v_and_b32_e32 v174, 15, v195
	v_lshl_add_u32 v173, v174, 2, v173
	v_add_u32_e32 v173, s17, v173
	v_mul_u32_u24_e32 v173, 0x2c00, v173
	v_lshl_add_u32 v173, v170, 1, v173
	v_add_u32_e32 v174, 0x160000, v173
	s_waitcnt vmcnt(0)
; __device__ __forceinline__ void st_bf4(bf16_t* p, f32x4 v) { u32x2 w; w.x = pk2(v[0], v[1]); w.y = pk2(v[2], v[3]); *(u32x2*)p = w; }
; __device__ __forceinline__ float sigmoidf_(float x) { return __builtin_amdgcn_rcpf(1.f + __expf(-x)); }
; __device__ __forceinline__ float dpp_ror1(float v) { return __int_as_float(__builtin_amdgcn_update_dpp(0, __float_as_int(v), 0x121, 0xf, 0xf, false)); }
; __device__ __forceinline__ float dpp_rol1(float v) { return __int_as_float(__builtin_amdgcn_update_dpp(0, __float_as_int(v), 0x12F, 0xf, 0xf, false)); }
;     __device__ __forceinline__ void tile(const f32x4 (&acc)[2][2][4][2], const Unit& u, int wr, int wc, int fr, int fq) const {
;     ...
;             const int cv = 128 * u.pn + 32 * wc + 16 * n + 4 * fq, cg = FF + cv;
;             const f32x4 wv0 = *(const f32x4*)(cw + cv), wv1 = *(const f32x4*)(cw + F2 + cv), wv2 = *(const f32x4*)(cw + 2 * F2 + cv), bv = *(const f32x4*)(cb + cv);
;             const f32x4 wg0 = *(const f32x4*)(cw + cg), wg1 = *(const f32x4*)(cw + F2 + cg), wg2 = *(const f32x4*)(cw + 2 * F2 + cg), bg = *(const f32x4*)(cb + cg);
; #pragma unroll
;             for (int ai = 0; ai < 2; ++ai)
; #pragma unroll
;                 for (int m = 0; m < 4; ++m) {
;                     f32x4 r;
; #pragma unroll
;                     for (int i = 0; i < 4; ++i) {
;                         const float xv = acc[ai][0][m][n][i], xg = acc[ai][1][m][n][i];
;                         const float uv = m > 0 ? acc[ai][0][m > 0 ? m - 1 : 0][n][i] : 0.f, ug = m > 0 ? acc[ai][1][m > 0 ? m - 1 : 0][n][i] : 0.f;
;                         const float dv = m < 3 ? acc[ai][0][m < 3 ? m + 1 : 3][n][i] : 0.f, dg = m < 3 ? acc[ai][1][m < 3 ? m + 1 : 3][n][i] : 0.f;
;                         const float pv = dpp_ror1(fr == 15 ? uv : xv), pg = dpp_ror1(fr == 15 ? ug : xg);
;                         const float nv = dpp_rol1(fr == 0 ? dv : xv), ng = dpp_rol1(fr == 0 ? dg : xg);
;                         const float yv = wv0[i] * pv + wv1[i] * xv + wv2[i] * nv + bv[i];
;                         const float yg = wg0[i] * pg + wg1[i] * xg + wg2[i] * ng + bg[i];
;                         r[i] = yg * sigmoidf_(yg) * yv;
;                     }
;                     st_bf4(ACT + (size_t)(u.pm * BM + ai * HALF + wr * 64 + m * 16 + fr) * FF + cv, r);
	v_mov_b32_dpp v216, v96 row_shr:1 row_mask:0xf bank_mask:0xf bound_ctrl:1
	v_mov_b32_dpp v217, v97 row_shr:1 row_mask:0xf bank_mask:0xf bound_ctrl:1
	v_mov_b32_dpp v218, v98 row_shr:1 row_mask:0xf bank_mask:0xf bound_ctrl:1
	v_mov_b32_dpp v219, v99 row_shr:1 row_mask:0xf bank_mask:0xf bound_ctrl:1
	v_mov_b32_dpp v220, v152 row_shl:1 row_mask:0xf bank_mask:0xf bound_ctrl:1
	v_mov_b32_dpp v221, v153 row_shl:1 row_mask:0xf bank_mask:0xf bound_ctrl:1
	v_mov_b32_dpp v222, v154 row_shl:1 row_mask:0xf bank_mask:0xf bound_ctrl:1
	v_mov_b32_dpp v223, v155 row_shl:1 row_mask:0xf bank_mask:0xf bound_ctrl:1
	v_pk_mul_f32 v[176:177], v[152:153], v[140:141]
	v_pk_mul_f32 v[178:179], v[154:155], v[142:143]
	v_pk_mul_f32 v[180:181], v[112:113], v[140:141]
	v_pk_mul_f32 v[182:183], v[114:115], v[142:143]
	v_pk_mul_f32 v[184:185], v[104:105], v[140:141]
	v_pk_mul_f32 v[186:187], v[106:107], v[142:143]
	v_pk_mul_f32 v[224:225], v[96:97], v[140:141]
	v_pk_mul_f32 v[226:227], v[98:99], v[142:143]
	v_pk_fma_f32 v[176:177], v[136:137], v[216:217], v[176:177]
	v_pk_fma_f32 v[178:179], v[138:139], v[218:219], v[178:179]
	v_pk_fma_f32 v[180:181], v[136:137], v[152:153], v[180:181]
	v_pk_fma_f32 v[182:183], v[138:139], v[154:155], v[182:183]
	v_pk_fma_f32 v[184:185], v[136:137], v[112:113], v[184:185]
	v_pk_fma_f32 v[186:187], v[138:139], v[114:115], v[186:187]
	v_pk_fma_f32 v[224:225], v[136:137], v[104:105], v[224:225]
	v_pk_fma_f32 v[226:227], v[138:139], v[106:107], v[226:227]
	v_pk_fma_f32 v[176:177], v[144:145], v[112:113], v[176:177]
	v_pk_fma_f32 v[178:179], v[146:147], v[114:115], v[178:179]
	v_pk_fma_f32 v[180:181], v[144:145], v[104:105], v[180:181]
	v_pk_fma_f32 v[182:183], v[146:147], v[106:107], v[182:183]
	v_pk_fma_f32 v[184:185], v[144:145], v[96:97], v[184:185]
	v_pk_fma_f32 v[186:187], v[146:147], v[98:99], v[186:187]
	v_pk_fma_f32 v[224:225], v[144:145], v[220:221], v[224:225]
	v_pk_fma_f32 v[226:227], v[146:147], v[222:223], v[226:227]
	v_pk_add_f32 v[176:177], v[148:149], v[176:177]
	v_pk_add_f32 v[178:179], v[150:151], v[178:179]
	v_pk_add_f32 v[180:181], v[148:149], v[180:181]
	v_pk_add_f32 v[182:183], v[150:151], v[182:183]
	v_pk_add_f32 v[184:185], v[148:149], v[184:185]
	v_pk_add_f32 v[186:187], v[150:151], v[186:187]
	v_pk_add_f32 v[224:225], v[148:149], v[224:225]
	v_pk_add_f32 v[226:227], v[150:151], v[226:227]
	v_mov_b32_dpp v216, v100 row_shr:1 row_mask:0xf bank_mask:0xf bound_ctrl:1
	v_mov_b32_dpp v217, v101 row_shr:1 row_mask:0xf bank_mask:0xf bound_ctrl:1
	v_mov_b32_dpp v218, v102 row_shr:1 row_mask:0xf bank_mask:0xf bound_ctrl:1
	v_mov_b32_dpp v219, v103 row_shr:1 row_mask:0xf bank_mask:0xf bound_ctrl:1
	v_mov_b32_dpp v220, v156 row_shl:1 row_mask:0xf bank_mask:0xf bound_ctrl:1
	v_mov_b32_dpp v221, v157 row_shl:1 row_mask:0xf bank_mask:0xf bound_ctrl:1
	v_mov_b32_dpp v222, v158 row_shl:1 row_mask:0xf bank_mask:0xf bound_ctrl:1
	v_mov_b32_dpp v223, v159 row_shl:1 row_mask:0xf bank_mask:0xf bound_ctrl:1
	v_pk_mul_f32 v[152:153], v[156:157], v[124:125]
	v_pk_mul_f32 v[154:155], v[158:159], v[126:127]
	v_pk_mul_f32 v[112:113], v[116:117], v[124:125]
	v_pk_mul_f32 v[114:115], v[118:119], v[126:127]
	v_pk_mul_f32 v[104:105], v[108:109], v[124:125]
	v_pk_mul_f32 v[106:107], v[110:111], v[126:127]
	v_pk_mul_f32 v[96:97], v[100:101], v[124:125]
	v_pk_mul_f32 v[98:99], v[102:103], v[126:127]
	v_pk_fma_f32 v[152:153], v[120:121], v[216:217], v[152:153]
	v_pk_fma_f32 v[154:155], v[122:123], v[218:219], v[154:155]
	v_pk_fma_f32 v[112:113], v[120:121], v[156:157], v[112:113]
	v_pk_fma_f32 v[114:115], v[122:123], v[158:159], v[114:115]
	v_pk_fma_f32 v[104:105], v[120:121], v[116:117], v[104:105]
	v_pk_fma_f32 v[106:107], v[122:123], v[118:119], v[106:107]
	v_pk_fma_f32 v[96:97], v[120:121], v[108:109], v[96:97]
	v_pk_fma_f32 v[98:99], v[122:123], v[110:111], v[98:99]
	v_pk_fma_f32 v[152:153], v[128:129], v[116:117], v[152:153]
	v_pk_fma_f32 v[154:155], v[130:131], v[118:119], v[154:155]
	v_pk_fma_f32 v[112:113], v[128:129], v[108:109], v[112:113]
	v_pk_fma_f32 v[114:115], v[130:131], v[110:111], v[114:115]
	v_pk_fma_f32 v[104:105], v[128:129], v[100:101], v[104:105]
	v_pk_fma_f32 v[106:107], v[130:131], v[102:103], v[106:107]
	v_pk_fma_f32 v[96:97], v[128:129], v[220:221], v[96:97]
	v_pk_fma_f32 v[98:99], v[130:131], v[222:223], v[98:99]
	v_pk_add_f32 v[152:153], v[132:133], v[152:153]
	v_pk_add_f32 v[154:155], v[134:135], v[154:155]
	v_pk_add_f32 v[112:113], v[132:133], v[112:113]
	v_pk_add_f32 v[114:115], v[134:135], v[114:115]
	v_pk_add_f32 v[104:105], v[132:133], v[104:105]
	v_pk_add_f32 v[106:107], v[134:135], v[106:107]
	v_pk_add_f32 v[96:97], v[132:133], v[96:97]
	v_pk_add_f32 v[98:99], v[134:135], v[98:99]
	v_mul_f32_e32 v156, 0xbfb8aa3b, v176
	v_mul_f32_e32 v157, 0xbfb8aa3b, v177
	v_mul_f32_e32 v158, 0xbfb8aa3b, v178
	v_mul_f32_e32 v159, 0xbfb8aa3b, v179
	v_mul_f32_e32 v116, 0xbfb8aa3b, v180
	v_mul_f32_e32 v117, 0xbfb8aa3b, v181
	v_mul_f32_e32 v118, 0xbfb8aa3b, v182
	v_mul_f32_e32 v119, 0xbfb8aa3b, v183
	v_mul_f32_e32 v108, 0xbfb8aa3b, v184
	v_mul_f32_e32 v109, 0xbfb8aa3b, v185
	v_mul_f32_e32 v110, 0xbfb8aa3b, v186
	v_mul_f32_e32 v111, 0xbfb8aa3b, v187
	v_mul_f32_e32 v100, 0xbfb8aa3b, v224
	v_mul_f32_e32 v101, 0xbfb8aa3b, v225
	v_mul_f32_e32 v102, 0xbfb8aa3b, v226
	v_mul_f32_e32 v103, 0xbfb8aa3b, v227
	v_exp_f32_e32 v156, v156
	v_exp_f32_e32 v157, v157
	v_exp_f32_e32 v158, v158
	v_exp_f32_e32 v159, v159
	v_exp_f32_e32 v116, v116
	v_exp_f32_e32 v117, v117
	v_exp_f32_e32 v118, v118
	v_exp_f32_e32 v119, v119
	v_exp_f32_e32 v108, v108
	v_exp_f32_e32 v109, v109
	v_exp_f32_e32 v110, v110
	v_exp_f32_e32 v111, v111
	v_exp_f32_e32 v100, v100
; __device__ __forceinline__ void st_bf4(bf16_t* p, f32x4 v) { u32x2 w; w.x = pk2(v[0], v[1]); w.y = pk2(v[2], v[3]); *(u32x2*)p = w; }
; __device__ __forceinline__ float sigmoidf_(float x) { return __builtin_amdgcn_rcpf(1.f + __expf(-x)); }
; __device__ __forceinline__ float dpp_ror1(float v) { return __int_as_float(__builtin_amdgcn_update_dpp(0, __float_as_int(v), 0x121, 0xf, 0xf, false)); }
; __device__ __forceinline__ float dpp_rol1(float v) { return __int_as_float(__builtin_amdgcn_update_dpp(0, __float_as_int(v), 0x12F, 0xf, 0xf, false)); }
;     __device__ __forceinline__ void tile(const f32x4 (&acc)[2][2][4][2], const Unit& u, int wr, int wc, int fr, int fq) const {
;     ...
;             const int cv = 128 * u.pn + 32 * wc + 16 * n + 4 * fq, cg = FF + cv;
;             const f32x4 wv0 = *(const f32x4*)(cw + cv), wv1 = *(const f32x4*)(cw + F2 + cv), wv2 = *(const f32x4*)(cw + 2 * F2 + cv), bv = *(const f32x4*)(cb + cv);
;             const f32x4 wg0 = *(const f32x4*)(cw + cg), wg1 = *(const f32x4*)(cw + F2 + cg), wg2 = *(const f32x4*)(cw + 2 * F2 + cg), bg = *(const f32x4*)(cb + cg);
; #pragma unroll
;             for (int ai = 0; ai < 2; ++ai)
; #pragma unroll
;                 for (int m = 0; m < 4; ++m) {
;                     f32x4 r;
; #pragma unroll
;                     for (int i = 0; i < 4; ++i) {
;                         const float xv = acc[ai][0][m][n][i], xg = acc[ai][1][m][n][i];
;                         const float uv = m > 0 ? acc[ai][0][m > 0 ? m - 1 : 0][n][i] : 0.f, ug = m > 0 ? acc[ai][1][m > 0 ? m - 1 : 0][n][i] : 0.f;
;                         const float dv = m < 3 ? acc[ai][0][m < 3 ? m + 1 : 3][n][i] : 0.f, dg = m < 3 ? acc[ai][1][m < 3 ? m + 1 : 3][n][i] : 0.f;
;                         const float pv = dpp_ror1(fr == 15 ? uv : xv), pg = dpp_ror1(fr == 15 ? ug : xg);
;                         const float nv = dpp_rol1(fr == 0 ? dv : xv), ng = dpp_rol1(fr == 0 ? dg : xg);
;                         const float yv = wv0[i] * pv + wv1[i] * xv + wv2[i] * nv + bv[i];
;                         const float yg = wg0[i] * pg + wg1[i] * xg + wg2[i] * ng + bg[i];
;                         r[i] = yg * sigmoidf_(yg) * yv;
;                     }
;                     st_bf4(ACT + (size_t)(u.pm * BM + ai * HALF + wr * 64 + m * 16 + fr) * FF + cv, r);
	v_exp_f32_e32 v101, v101
	v_exp_f32_e32 v102, v102
	v_exp_f32_e32 v103, v103
	v_add_f32_e32 v156, 1.0, v156
	v_add_f32_e32 v157, 1.0, v157
	v_add_f32_e32 v158, 1.0, v158
	v_add_f32_e32 v159, 1.0, v159
	v_add_f32_e32 v116, 1.0, v116
	v_add_f32_e32 v117, 1.0, v117
	v_add_f32_e32 v118, 1.0, v118
	v_add_f32_e32 v119, 1.0, v119
	v_add_f32_e32 v108, 1.0, v108
	v_add_f32_e32 v109, 1.0, v109
	v_add_f32_e32 v110, 1.0, v110
	v_add_f32_e32 v111, 1.0, v111
	v_add_f32_e32 v100, 1.0, v100
	v_add_f32_e32 v101, 1.0, v101
	v_add_f32_e32 v102, 1.0, v102
	v_add_f32_e32 v103, 1.0, v103
	v_rcp_f32_e32 v156, v156
	v_rcp_f32_e32 v157, v157
	v_rcp_f32_e32 v158, v158
	v_rcp_f32_e32 v159, v159
	v_rcp_f32_e32 v116, v116
	v_rcp_f32_e32 v117, v117
	v_rcp_f32_e32 v118, v118
	v_rcp_f32_e32 v119, v119
	v_rcp_f32_e32 v108, v108
	v_rcp_f32_e32 v109, v109
	v_rcp_f32_e32 v110, v110
	v_rcp_f32_e32 v111, v111
	v_rcp_f32_e32 v100, v100
	v_rcp_f32_e32 v101, v101
	v_rcp_f32_e32 v102, v102
	v_rcp_f32_e32 v103, v103
	v_pk_mul_f32 v[176:177], v[176:177], v[156:157]
	v_pk_mul_f32 v[178:179], v[178:179], v[158:159]
	v_pk_mul_f32 v[180:181], v[180:181], v[116:117]
	v_pk_mul_f32 v[182:183], v[182:183], v[118:119]
	v_pk_mul_f32 v[184:185], v[184:185], v[108:109]
	v_pk_mul_f32 v[186:187], v[186:187], v[110:111]
	v_pk_mul_f32 v[224:225], v[224:225], v[100:101]
	v_pk_mul_f32 v[226:227], v[226:227], v[102:103]
	v_pk_mul_f32 v[176:177], v[152:153], v[176:177]
	v_pk_mul_f32 v[178:179], v[154:155], v[178:179]
	v_pk_mul_f32 v[180:181], v[112:113], v[180:181]
	v_pk_mul_f32 v[182:183], v[114:115], v[182:183]
	v_pk_mul_f32 v[184:185], v[104:105], v[184:185]
	v_pk_mul_f32 v[186:187], v[106:107], v[186:187]
	v_pk_mul_f32 v[224:225], v[96:97], v[224:225]
	v_pk_mul_f32 v[226:227], v[98:99], v[226:227]
	v_cvt_pk_bf16_f32 v156, v176, v177
	v_cvt_pk_bf16_f32 v157, v178, v179
	v_cvt_pk_bf16_f32 v116, v180, v181
	v_cvt_pk_bf16_f32 v117, v182, v183
	v_cvt_pk_bf16_f32 v108, v184, v185
	v_cvt_pk_bf16_f32 v109, v186, v187
	v_cvt_pk_bf16_f32 v100, v224, v225
	v_cvt_pk_bf16_f32 v101, v226, v227
	global_store_dwordx2 v173, v[156:157], s[0:1]
	v_add_u32_e32 v175, 0x2c00, v173
	global_store_dwordx2 v175, v[116:117], s[0:1]
	v_add_u32_e32 v175, 0x5800, v173
	global_store_dwordx2 v175, v[108:109], s[0:1]
	v_add_u32_e32 v175, 0x8400, v173
	global_store_dwordx2 v175, v[100:101], s[0:1]
	v_mov_b32_dpp v216, v64 row_shr:1 row_mask:0xf bank_mask:0xf bound_ctrl:1
	v_mov_b32_dpp v217, v65 row_shr:1 row_mask:0xf bank_mask:0xf bound_ctrl:1
	v_mov_b32_dpp v218, v66 row_shr:1 row_mask:0xf bank_mask:0xf bound_ctrl:1
	v_mov_b32_dpp v219, v67 row_shr:1 row_mask:0xf bank_mask:0xf bound_ctrl:1
	v_mov_b32_dpp v220, v88 row_shl:1 row_mask:0xf bank_mask:0xf bound_ctrl:1
	v_mov_b32_dpp v221, v89 row_shl:1 row_mask:0xf bank_mask:0xf bound_ctrl:1
	v_mov_b32_dpp v222, v90 row_shl:1 row_mask:0xf bank_mask:0xf bound_ctrl:1
	v_mov_b32_dpp v223, v91 row_shl:1 row_mask:0xf bank_mask:0xf bound_ctrl:1
	v_pk_mul_f32 v[176:177], v[88:89], v[140:141]
	v_pk_mul_f32 v[178:179], v[90:91], v[142:143]
	v_pk_mul_f32 v[180:181], v[80:81], v[140:141]
	v_pk_mul_f32 v[182:183], v[82:83], v[142:143]
	v_pk_mul_f32 v[184:185], v[72:73], v[140:141]
	v_pk_mul_f32 v[186:187], v[74:75], v[142:143]
	v_pk_mul_f32 v[224:225], v[64:65], v[140:141]
	v_pk_mul_f32 v[226:227], v[66:67], v[142:143]
	v_pk_fma_f32 v[176:177], v[136:137], v[216:217], v[176:177]
	v_pk_fma_f32 v[178:179], v[138:139], v[218:219], v[178:179]
	v_pk_fma_f32 v[180:181], v[136:137], v[88:89], v[180:181]
	v_pk_fma_f32 v[182:183], v[138:139], v[90:91], v[182:183]
	v_pk_fma_f32 v[184:185], v[136:137], v[80:81], v[184:185]
	v_pk_fma_f32 v[186:187], v[138:139], v[82:83], v[186:187]
	v_pk_fma_f32 v[224:225], v[136:137], v[72:73], v[224:225]
	v_pk_fma_f32 v[226:227], v[138:139], v[74:75], v[226:227]
	v_pk_fma_f32 v[176:177], v[144:145], v[80:81], v[176:177]
	v_pk_fma_f32 v[178:179], v[146:147], v[82:83], v[178:179]
	v_pk_fma_f32 v[180:181], v[144:145], v[72:73], v[180:181]
	v_pk_fma_f32 v[182:183], v[146:147], v[74:75], v[182:183]
	v_pk_fma_f32 v[184:185], v[144:145], v[64:65], v[184:185]
	v_pk_fma_f32 v[186:187], v[146:147], v[66:67], v[186:187]
	v_pk_fma_f32 v[224:225], v[144:145], v[220:221], v[224:225]
	v_pk_fma_f32 v[226:227], v[146:147], v[222:223], v[226:227]
	v_pk_add_f32 v[176:177], v[148:149], v[176:177]
	v_pk_add_f32 v[178:179], v[150:151], v[178:179]
	v_pk_add_f32 v[180:181], v[148:149], v[180:181]
	v_pk_add_f32 v[182:183], v[150:151], v[182:183]
	v_pk_add_f32 v[184:185], v[148:149], v[184:185]
	v_pk_add_f32 v[186:187], v[150:151], v[186:187]
	v_pk_add_f32 v[224:225], v[148:149], v[224:225]
	v_pk_add_f32 v[226:227], v[150:151], v[226:227]
	v_mov_b32_dpp v216, v68 row_shr:1 row_mask:0xf bank_mask:0xf bound_ctrl:1
	v_mov_b32_dpp v217, v69 row_shr:1 row_mask:0xf bank_mask:0xf bound_ctrl:1
	v_mov_b32_dpp v218, v70 row_shr:1 row_mask:0xf bank_mask:0xf bound_ctrl:1
	v_mov_b32_dpp v219, v71 row_shr:1 row_mask:0xf bank_mask:0xf bound_ctrl:1
	v_mov_b32_dpp v220, v92 row_shl:1 row_mask:0xf bank_mask:0xf bound_ctrl:1
	v_mov_b32_dpp v221, v93 row_shl:1 row_mask:0xf bank_mask:0xf bound_ctrl:1
	v_mov_b32_dpp v222, v94 row_shl:1 row_mask:0xf bank_mask:0xf bound_ctrl:1
	v_mov_b32_dpp v223, v95 row_shl:1 row_mask:0xf bank_mask:0xf bound_ctrl:1
	v_pk_mul_f32 v[88:89], v[92:93], v[124:125]
	v_pk_mul_f32 v[90:91], v[94:95], v[126:127]
	v_pk_mul_f32 v[80:81], v[84:85], v[124:125]
	v_pk_mul_f32 v[82:83], v[86:87], v[126:127]
	v_pk_mul_f32 v[72:73], v[76:77], v[124:125]
	v_pk_mul_f32 v[74:75], v[78:79], v[126:127]
	v_pk_mul_f32 v[64:65], v[68:69], v[124:125]
	v_pk_mul_f32 v[66:67], v[70:71], v[126:127]
; __device__ __forceinline__ void st_bf4(bf16_t* p, f32x4 v) { u32x2 w; w.x = pk2(v[0], v[1]); w.y = pk2(v[2], v[3]); *(u32x2*)p = w; }
; __device__ __forceinline__ float sigmoidf_(float x) { return __builtin_amdgcn_rcpf(1.f + __expf(-x)); }
; __device__ __forceinline__ float dpp_ror1(float v) { return __int_as_float(__builtin_amdgcn_update_dpp(0, __float_as_int(v), 0x121, 0xf, 0xf, false)); }
; __device__ __forceinline__ float dpp_rol1(float v) { return __int_as_float(__builtin_amdgcn_update_dpp(0, __float_as_int(v), 0x12F, 0xf, 0xf, false)); }
;     __device__ __forceinline__ void tile(const f32x4 (&acc)[2][2][4][2], const Unit& u, int wr, int wc, int fr, int fq) const {
;     ...
;             const int cv = 128 * u.pn + 32 * wc + 16 * n + 4 * fq, cg = FF + cv;
;             const f32x4 wv0 = *(const f32x4*)(cw + cv), wv1 = *(const f32x4*)(cw + F2 + cv), wv2 = *(const f32x4*)(cw + 2 * F2 + cv), bv = *(const f32x4*)(cb + cv);
;             const f32x4 wg0 = *(const f32x4*)(cw + cg), wg1 = *(const f32x4*)(cw + F2 + cg), wg2 = *(const f32x4*)(cw + 2 * F2 + cg), bg = *(const f32x4*)(cb + cg);
; #pragma unroll
;             for (int ai = 0; ai < 2; ++ai)
; #pragma unroll
;                 for (int m = 0; m < 4; ++m) {
;                     f32x4 r;
; #pragma unroll
;                     for (int i = 0; i < 4; ++i) {
;                         const float xv = acc[ai][0][m][n][i], xg = acc[ai][1][m][n][i];
;                         const float uv = m > 0 ? acc[ai][0][m > 0 ? m - 1 : 0][n][i] : 0.f, ug = m > 0 ? acc[ai][1][m > 0 ? m - 1 : 0][n][i] : 0.f;
;                         const float dv = m < 3 ? acc[ai][0][m < 3 ? m + 1 : 3][n][i] : 0.f, dg = m < 3 ? acc[ai][1][m < 3 ? m + 1 : 3][n][i] : 0.f;
;                         const float pv = dpp_ror1(fr == 15 ? uv : xv), pg = dpp_ror1(fr == 15 ? ug : xg);
;                         const float nv = dpp_rol1(fr == 0 ? dv : xv), ng = dpp_rol1(fr == 0 ? dg : xg);
;                         const float yv = wv0[i] * pv + wv1[i] * xv + wv2[i] * nv + bv[i];
;                         const float yg = wg0[i] * pg + wg1[i] * xg + wg2[i] * ng + bg[i];
;                         r[i] = yg * sigmoidf_(yg) * yv;
;                     }
;                     st_bf4(ACT + (size_t)(u.pm * BM + ai * HALF + wr * 64 + m * 16 + fr) * FF + cv, r);
	v_pk_fma_f32 v[88:89], v[120:121], v[216:217], v[88:89]
	v_pk_fma_f32 v[90:91], v[122:123], v[218:219], v[90:91]
	v_pk_fma_f32 v[80:81], v[120:121], v[92:93], v[80:81]
	v_pk_fma_f32 v[82:83], v[122:123], v[94:95], v[82:83]
	v_pk_fma_f32 v[72:73], v[120:121], v[84:85], v[72:73]
	v_pk_fma_f32 v[74:75], v[122:123], v[86:87], v[74:75]
	v_pk_fma_f32 v[64:65], v[120:121], v[76:77], v[64:65]
	v_pk_fma_f32 v[66:67], v[122:123], v[78:79], v[66:67]
	v_pk_fma_f32 v[88:89], v[128:129], v[84:85], v[88:89]
	v_pk_fma_f32 v[90:91], v[130:131], v[86:87], v[90:91]
	v_pk_fma_f32 v[80:81], v[128:129], v[76:77], v[80:81]
	v_pk_fma_f32 v[82:83], v[130:131], v[78:79], v[82:83]
	v_pk_fma_f32 v[72:73], v[128:129], v[68:69], v[72:73]
	v_pk_fma_f32 v[74:75], v[130:131], v[70:71], v[74:75]
	v_pk_fma_f32 v[64:65], v[128:129], v[220:221], v[64:65]
	v_pk_fma_f32 v[66:67], v[130:131], v[222:223], v[66:67]
	v_pk_add_f32 v[88:89], v[132:133], v[88:89]
	v_pk_add_f32 v[90:91], v[134:135], v[90:91]
	v_pk_add_f32 v[80:81], v[132:133], v[80:81]
	v_pk_add_f32 v[82:83], v[134:135], v[82:83]
	v_pk_add_f32 v[72:73], v[132:133], v[72:73]
	v_pk_add_f32 v[74:75], v[134:135], v[74:75]
	v_pk_add_f32 v[64:65], v[132:133], v[64:65]
	v_pk_add_f32 v[66:67], v[134:135], v[66:67]
	v_mul_f32_e32 v92, 0xbfb8aa3b, v176
	v_mul_f32_e32 v93, 0xbfb8aa3b, v177
	v_mul_f32_e32 v94, 0xbfb8aa3b, v178
	v_mul_f32_e32 v95, 0xbfb8aa3b, v179
	v_mul_f32_e32 v84, 0xbfb8aa3b, v180
	v_mul_f32_e32 v85, 0xbfb8aa3b, v181
	v_mul_f32_e32 v86, 0xbfb8aa3b, v182
	v_mul_f32_e32 v87, 0xbfb8aa3b, v183
	v_mul_f32_e32 v76, 0xbfb8aa3b, v184
	v_mul_f32_e32 v77, 0xbfb8aa3b, v185
	v_mul_f32_e32 v78, 0xbfb8aa3b, v186
	v_mul_f32_e32 v79, 0xbfb8aa3b, v187
	v_mul_f32_e32 v68, 0xbfb8aa3b, v224
	v_mul_f32_e32 v69, 0xbfb8aa3b, v225
	v_mul_f32_e32 v70, 0xbfb8aa3b, v226
	v_mul_f32_e32 v71, 0xbfb8aa3b, v227
	v_exp_f32_e32 v92, v92
	v_exp_f32_e32 v93, v93
	v_exp_f32_e32 v94, v94
	v_exp_f32_e32 v95, v95
	v_exp_f32_e32 v84, v84
	v_exp_f32_e32 v85, v85
	v_exp_f32_e32 v86, v86
	v_exp_f32_e32 v87, v87
	v_exp_f32_e32 v76, v76
	v_exp_f32_e32 v77, v77
	v_exp_f32_e32 v78, v78
	v_exp_f32_e32 v79, v79
	v_exp_f32_e32 v68, v68
	v_exp_f32_e32 v69, v69
	v_exp_f32_e32 v70, v70
	v_exp_f32_e32 v71, v71
	v_add_f32_e32 v92, 1.0, v92
	v_add_f32_e32 v93, 1.0, v93
	v_add_f32_e32 v94, 1.0, v94
	v_add_f32_e32 v95, 1.0, v95
	v_add_f32_e32 v84, 1.0, v84
	v_add_f32_e32 v85, 1.0, v85
	v_add_f32_e32 v86, 1.0, v86
	v_add_f32_e32 v87, 1.0, v87
	v_add_f32_e32 v76, 1.0, v76
	v_add_f32_e32 v77, 1.0, v77
	v_add_f32_e32 v78, 1.0, v78
	v_add_f32_e32 v79, 1.0, v79
	v_add_f32_e32 v68, 1.0, v68
	v_add_f32_e32 v69, 1.0, v69
	v_add_f32_e32 v70, 1.0, v70
	v_add_f32_e32 v71, 1.0, v71
	v_rcp_f32_e32 v92, v92
	v_rcp_f32_e32 v93, v93
	v_rcp_f32_e32 v94, v94
	v_rcp_f32_e32 v95, v95
	v_rcp_f32_e32 v84, v84
	v_rcp_f32_e32 v85, v85
	v_rcp_f32_e32 v86, v86
	v_rcp_f32_e32 v87, v87
	v_rcp_f32_e32 v76, v76
	v_rcp_f32_e32 v77, v77
	v_rcp_f32_e32 v78, v78
	v_rcp_f32_e32 v79, v79
	v_rcp_f32_e32 v68, v68
	v_rcp_f32_e32 v69, v69
	v_rcp_f32_e32 v70, v70
	v_rcp_f32_e32 v71, v71
	v_pk_mul_f32 v[176:177], v[176:177], v[92:93]
	v_pk_mul_f32 v[178:179], v[178:179], v[94:95]
	v_pk_mul_f32 v[180:181], v[180:181], v[84:85]
	v_pk_mul_f32 v[182:183], v[182:183], v[86:87]
	v_pk_mul_f32 v[184:185], v[184:185], v[76:77]
	v_pk_mul_f32 v[186:187], v[186:187], v[78:79]
	v_pk_mul_f32 v[224:225], v[224:225], v[68:69]
	v_pk_mul_f32 v[226:227], v[226:227], v[70:71]
	v_pk_mul_f32 v[176:177], v[88:89], v[176:177]
	v_pk_mul_f32 v[178:179], v[90:91], v[178:179]
	v_pk_mul_f32 v[180:181], v[80:81], v[180:181]
	v_pk_mul_f32 v[182:183], v[82:83], v[182:183]
	v_pk_mul_f32 v[184:185], v[72:73], v[184:185]
	v_pk_mul_f32 v[186:187], v[74:75], v[186:187]
	v_pk_mul_f32 v[224:225], v[64:65], v[224:225]
	v_pk_mul_f32 v[226:227], v[66:67], v[226:227]
	v_cvt_pk_bf16_f32 v92, v176, v177
	v_cvt_pk_bf16_f32 v93, v178, v179
	v_cvt_pk_bf16_f32 v84, v180, v181
	v_cvt_pk_bf16_f32 v85, v182, v183
	v_cvt_pk_bf16_f32 v76, v184, v185
	v_cvt_pk_bf16_f32 v77, v186, v187
	v_cvt_pk_bf16_f32 v68, v224, v225
	v_cvt_pk_bf16_f32 v69, v226, v227
	global_store_dwordx2 v174, v[92:93], s[0:1]
	v_add_u32_e32 v175, 0x2c00, v174
	global_store_dwordx2 v175, v[84:85], s[0:1]
	v_add_u32_e32 v175, 0x5800, v174
	global_store_dwordx2 v175, v[76:77], s[0:1]
	v_add_u32_e32 v175, 0x8400, v174
	global_store_dwordx2 v175, v[68:69], s[0:1]
	v_mov_b32_dpp v216, v32 row_shr:1 row_mask:0xf bank_mask:0xf bound_ctrl:1
	v_mov_b32_dpp v217, v33 row_shr:1 row_mask:0xf bank_mask:0xf bound_ctrl:1
	v_mov_b32_dpp v218, v34 row_shr:1 row_mask:0xf bank_mask:0xf bound_ctrl:1
	v_mov_b32_dpp v219, v35 row_shr:1 row_mask:0xf bank_mask:0xf bound_ctrl:1
	v_mov_b32_dpp v220, v56 row_shl:1 row_mask:0xf bank_mask:0xf bound_ctrl:1
	v_mov_b32_dpp v221, v57 row_shl:1 row_mask:0xf bank_mask:0xf bound_ctrl:1
	v_mov_b32_dpp v222, v58 row_shl:1 row_mask:0xf bank_mask:0xf bound_ctrl:1
	v_mov_b32_dpp v223, v59 row_shl:1 row_mask:0xf bank_mask:0xf bound_ctrl:1
	v_pk_mul_f32 v[176:177], v[56:57], v[250:251]
	v_pk_mul_f32 v[178:179], v[58:59], v[252:253]
	v_pk_mul_f32 v[180:181], v[48:49], v[250:251]
	v_pk_mul_f32 v[182:183], v[50:51], v[252:253]
	v_pk_mul_f32 v[184:185], v[40:41], v[250:251]
	v_pk_mul_f32 v[186:187], v[42:43], v[252:253]
	v_pk_mul_f32 v[224:225], v[32:33], v[250:251]
	v_pk_mul_f32 v[226:227], v[34:35], v[252:253]
	v_pk_fma_f32 v[176:177], v[246:247], v[216:217], v[176:177]
	v_pk_fma_f32 v[178:179], v[248:249], v[218:219], v[178:179]
	v_pk_fma_f32 v[180:181], v[246:247], v[56:57], v[180:181]
	v_pk_fma_f32 v[182:183], v[248:249], v[58:59], v[182:183]
	v_pk_fma_f32 v[184:185], v[246:247], v[48:49], v[184:185]
; __device__ __forceinline__ void st_bf4(bf16_t* p, f32x4 v) { u32x2 w; w.x = pk2(v[0], v[1]); w.y = pk2(v[2], v[3]); *(u32x2*)p = w; }
; __device__ __forceinline__ float sigmoidf_(float x) { return __builtin_amdgcn_rcpf(1.f + __expf(-x)); }
; __device__ __forceinline__ float dpp_ror1(float v) { return __int_as_float(__builtin_amdgcn_update_dpp(0, __float_as_int(v), 0x121, 0xf, 0xf, false)); }
; __device__ __forceinline__ float dpp_rol1(float v) { return __int_as_float(__builtin_amdgcn_update_dpp(0, __float_as_int(v), 0x12F, 0xf, 0xf, false)); }
;     __device__ __forceinline__ void tile(const f32x4 (&acc)[2][2][4][2], const Unit& u, int wr, int wc, int fr, int fq) const {
;     ...
;             const int cv = 128 * u.pn + 32 * wc + 16 * n + 4 * fq, cg = FF + cv;
;             const f32x4 wv0 = *(const f32x4*)(cw + cv), wv1 = *(const f32x4*)(cw + F2 + cv), wv2 = *(const f32x4*)(cw + 2 * F2 + cv), bv = *(const f32x4*)(cb + cv);
;             const f32x4 wg0 = *(const f32x4*)(cw + cg), wg1 = *(const f32x4*)(cw + F2 + cg), wg2 = *(const f32x4*)(cw + 2 * F2 + cg), bg = *(const f32x4*)(cb + cg);
; #pragma unroll
;             for (int ai = 0; ai < 2; ++ai)
; #pragma unroll
;                 for (int m = 0; m < 4; ++m) {
;                     f32x4 r;
; #pragma unroll
;                     for (int i = 0; i < 4; ++i) {
;                         const float xv = acc[ai][0][m][n][i], xg = acc[ai][1][m][n][i];
;                         const float uv = m > 0 ? acc[ai][0][m > 0 ? m - 1 : 0][n][i] : 0.f, ug = m > 0 ? acc[ai][1][m > 0 ? m - 1 : 0][n][i] : 0.f;
;                         const float dv = m < 3 ? acc[ai][0][m < 3 ? m + 1 : 3][n][i] : 0.f, dg = m < 3 ? acc[ai][1][m < 3 ? m + 1 : 3][n][i] : 0.f;
;                         const float pv = dpp_ror1(fr == 15 ? uv : xv), pg = dpp_ror1(fr == 15 ? ug : xg);
;                         const float nv = dpp_rol1(fr == 0 ? dv : xv), ng = dpp_rol1(fr == 0 ? dg : xg);
;                         const float yv = wv0[i] * pv + wv1[i] * xv + wv2[i] * nv + bv[i];
;                         const float yg = wg0[i] * pg + wg1[i] * xg + wg2[i] * ng + bg[i];
;                         r[i] = yg * sigmoidf_(yg) * yv;
;                     }
;                     st_bf4(ACT + (size_t)(u.pm * BM + ai * HALF + wr * 64 + m * 16 + fr) * FF + cv, r);
	v_pk_fma_f32 v[186:187], v[248:249], v[50:51], v[186:187]
	v_pk_fma_f32 v[224:225], v[246:247], v[40:41], v[224:225]
	v_pk_fma_f32 v[226:227], v[248:249], v[42:43], v[226:227]
	v_pk_fma_f32 v[176:177], v[208:209], v[48:49], v[176:177]
	v_pk_fma_f32 v[178:179], v[210:211], v[50:51], v[178:179]
	v_pk_fma_f32 v[180:181], v[208:209], v[40:41], v[180:181]
	v_pk_fma_f32 v[182:183], v[210:211], v[42:43], v[182:183]
	v_pk_fma_f32 v[184:185], v[208:209], v[32:33], v[184:185]
	v_pk_fma_f32 v[186:187], v[210:211], v[34:35], v[186:187]
	v_pk_fma_f32 v[224:225], v[208:209], v[220:221], v[224:225]
	v_pk_fma_f32 v[226:227], v[210:211], v[222:223], v[226:227]
	v_pk_add_f32 v[176:177], v[212:213], v[176:177]
	v_pk_add_f32 v[178:179], v[214:215], v[178:179]
	v_pk_add_f32 v[180:181], v[212:213], v[180:181]
	v_pk_add_f32 v[182:183], v[214:215], v[182:183]
	v_pk_add_f32 v[184:185], v[212:213], v[184:185]
	v_pk_add_f32 v[186:187], v[214:215], v[186:187]
	v_pk_add_f32 v[224:225], v[212:213], v[224:225]
	v_pk_add_f32 v[226:227], v[214:215], v[226:227]
	v_mov_b32_dpp v216, v36 row_shr:1 row_mask:0xf bank_mask:0xf bound_ctrl:1
	v_mov_b32_dpp v217, v37 row_shr:1 row_mask:0xf bank_mask:0xf bound_ctrl:1
	v_mov_b32_dpp v218, v38 row_shr:1 row_mask:0xf bank_mask:0xf bound_ctrl:1
	v_mov_b32_dpp v219, v39 row_shr:1 row_mask:0xf bank_mask:0xf bound_ctrl:1
	v_mov_b32_dpp v220, v60 row_shl:1 row_mask:0xf bank_mask:0xf bound_ctrl:1
	v_mov_b32_dpp v221, v61 row_shl:1 row_mask:0xf bank_mask:0xf bound_ctrl:1
	v_mov_b32_dpp v222, v62 row_shl:1 row_mask:0xf bank_mask:0xf bound_ctrl:1
	v_mov_b32_dpp v223, v63 row_shl:1 row_mask:0xf bank_mask:0xf bound_ctrl:1
	v_pk_mul_f32 v[56:57], v[60:61], v[234:235]
	v_pk_mul_f32 v[58:59], v[62:63], v[236:237]
	v_pk_mul_f32 v[48:49], v[52:53], v[234:235]
	v_pk_mul_f32 v[50:51], v[54:55], v[236:237]
	v_pk_mul_f32 v[40:41], v[44:45], v[234:235]
	v_pk_mul_f32 v[42:43], v[46:47], v[236:237]
	v_pk_mul_f32 v[32:33], v[36:37], v[234:235]
	v_pk_mul_f32 v[34:35], v[38:39], v[236:237]
	v_pk_fma_f32 v[56:57], v[230:231], v[216:217], v[56:57]
	v_pk_fma_f32 v[58:59], v[232:233], v[218:219], v[58:59]
	v_pk_fma_f32 v[48:49], v[230:231], v[60:61], v[48:49]
	v_pk_fma_f32 v[50:51], v[232:233], v[62:63], v[50:51]
	v_pk_fma_f32 v[40:41], v[230:231], v[52:53], v[40:41]
	v_pk_fma_f32 v[42:43], v[232:233], v[54:55], v[42:43]
	v_pk_fma_f32 v[32:33], v[230:231], v[44:45], v[32:33]
	v_pk_fma_f32 v[34:35], v[232:233], v[46:47], v[34:35]
	v_pk_fma_f32 v[56:57], v[238:239], v[52:53], v[56:57]
	v_pk_fma_f32 v[58:59], v[240:241], v[54:55], v[58:59]
	v_pk_fma_f32 v[48:49], v[238:239], v[44:45], v[48:49]
	v_pk_fma_f32 v[50:51], v[240:241], v[46:47], v[50:51]
	v_pk_fma_f32 v[40:41], v[238:239], v[36:37], v[40:41]
	v_pk_fma_f32 v[42:43], v[240:241], v[38:39], v[42:43]
	v_pk_fma_f32 v[32:33], v[238:239], v[220:221], v[32:33]
	v_pk_fma_f32 v[34:35], v[240:241], v[222:223], v[34:35]
	v_pk_add_f32 v[56:57], v[242:243], v[56:57]
	v_pk_add_f32 v[58:59], v[244:245], v[58:59]
	v_pk_add_f32 v[48:49], v[242:243], v[48:49]
	v_pk_add_f32 v[50:51], v[244:245], v[50:51]
	v_pk_add_f32 v[40:41], v[242:243], v[40:41]
	v_pk_add_f32 v[42:43], v[244:245], v[42:43]
	v_pk_add_f32 v[32:33], v[242:243], v[32:33]
	v_pk_add_f32 v[34:35], v[244:245], v[34:35]
	v_mul_f32_e32 v60, 0xbfb8aa3b, v176
	v_mul_f32_e32 v61, 0xbfb8aa3b, v177
	v_mul_f32_e32 v62, 0xbfb8aa3b, v178
	v_mul_f32_e32 v63, 0xbfb8aa3b, v179
	v_mul_f32_e32 v52, 0xbfb8aa3b, v180
	v_mul_f32_e32 v53, 0xbfb8aa3b, v181
	v_mul_f32_e32 v54, 0xbfb8aa3b, v182
	v_mul_f32_e32 v55, 0xbfb8aa3b, v183
	v_mul_f32_e32 v44, 0xbfb8aa3b, v184
	v_mul_f32_e32 v45, 0xbfb8aa3b, v185
	v_mul_f32_e32 v46, 0xbfb8aa3b, v186
	v_mul_f32_e32 v47, 0xbfb8aa3b, v187
	v_mul_f32_e32 v36, 0xbfb8aa3b, v224
	v_mul_f32_e32 v37, 0xbfb8aa3b, v225
	v_mul_f32_e32 v38, 0xbfb8aa3b, v226
	v_mul_f32_e32 v39, 0xbfb8aa3b, v227
	v_exp_f32_e32 v60, v60
	v_exp_f32_e32 v61, v61
	v_exp_f32_e32 v62, v62
	v_exp_f32_e32 v63, v63
	v_exp_f32_e32 v52, v52
	v_exp_f32_e32 v53, v53
	v_exp_f32_e32 v54, v54
	v_exp_f32_e32 v55, v55
	v_exp_f32_e32 v44, v44
	v_exp_f32_e32 v45, v45
	v_exp_f32_e32 v46, v46
	v_exp_f32_e32 v47, v47
	v_exp_f32_e32 v36, v36
	v_exp_f32_e32 v37, v37
	v_exp_f32_e32 v38, v38
	v_exp_f32_e32 v39, v39
	v_add_f32_e32 v60, 1.0, v60
	v_add_f32_e32 v61, 1.0, v61
	v_add_f32_e32 v62, 1.0, v62
	v_add_f32_e32 v63, 1.0, v63
	v_add_f32_e32 v52, 1.0, v52
	v_add_f32_e32 v53, 1.0, v53
	v_add_f32_e32 v54, 1.0, v54
	v_add_f32_e32 v55, 1.0, v55
	v_add_f32_e32 v44, 1.0, v44
	v_add_f32_e32 v45, 1.0, v45
	v_add_f32_e32 v46, 1.0, v46
	v_add_f32_e32 v47, 1.0, v47
	v_add_f32_e32 v36, 1.0, v36
	v_add_f32_e32 v37, 1.0, v37
	v_add_f32_e32 v38, 1.0, v38
	v_add_f32_e32 v39, 1.0, v39
	v_rcp_f32_e32 v60, v60
	v_rcp_f32_e32 v61, v61
	v_rcp_f32_e32 v62, v62
	v_rcp_f32_e32 v63, v63
	v_rcp_f32_e32 v52, v52
	v_rcp_f32_e32 v53, v53
	v_rcp_f32_e32 v54, v54
	v_rcp_f32_e32 v55, v55
	v_rcp_f32_e32 v44, v44
	v_rcp_f32_e32 v45, v45
	v_rcp_f32_e32 v46, v46
	v_rcp_f32_e32 v47, v47
	v_rcp_f32_e32 v36, v36
	v_rcp_f32_e32 v37, v37
	v_rcp_f32_e32 v38, v38
	v_rcp_f32_e32 v39, v39
	v_pk_mul_f32 v[176:177], v[176:177], v[60:61]
	v_pk_mul_f32 v[178:179], v[178:179], v[62:63]
	v_pk_mul_f32 v[180:181], v[180:181], v[52:53]
	v_pk_mul_f32 v[182:183], v[182:183], v[54:55]
	v_pk_mul_f32 v[184:185], v[184:185], v[44:45]
	v_pk_mul_f32 v[186:187], v[186:187], v[46:47]
	v_pk_mul_f32 v[224:225], v[224:225], v[36:37]
	v_pk_mul_f32 v[226:227], v[226:227], v[38:39]
	v_pk_mul_f32 v[176:177], v[56:57], v[176:177]
	v_pk_mul_f32 v[178:179], v[58:59], v[178:179]
	v_pk_mul_f32 v[180:181], v[48:49], v[180:181]
	v_pk_mul_f32 v[182:183], v[50:51], v[182:183]
; __device__ __forceinline__ void st_bf4(bf16_t* p, f32x4 v) { u32x2 w; w.x = pk2(v[0], v[1]); w.y = pk2(v[2], v[3]); *(u32x2*)p = w; }
; __device__ __forceinline__ float sigmoidf_(float x) { return __builtin_amdgcn_rcpf(1.f + __expf(-x)); }
; __device__ __forceinline__ float dpp_ror1(float v) { return __int_as_float(__builtin_amdgcn_update_dpp(0, __float_as_int(v), 0x121, 0xf, 0xf, false)); }
; __device__ __forceinline__ float dpp_rol1(float v) { return __int_as_float(__builtin_amdgcn_update_dpp(0, __float_as_int(v), 0x12F, 0xf, 0xf, false)); }
;     __device__ __forceinline__ void tile(const f32x4 (&acc)[2][2][4][2], const Unit& u, int wr, int wc, int fr, int fq) const {
;     ...
;             const int cv = 128 * u.pn + 32 * wc + 16 * n + 4 * fq, cg = FF + cv;
;             const f32x4 wv0 = *(const f32x4*)(cw + cv), wv1 = *(const f32x4*)(cw + F2 + cv), wv2 = *(const f32x4*)(cw + 2 * F2 + cv), bv = *(const f32x4*)(cb + cv);
;             const f32x4 wg0 = *(const f32x4*)(cw + cg), wg1 = *(const f32x4*)(cw + F2 + cg), wg2 = *(const f32x4*)(cw + 2 * F2 + cg), bg = *(const f32x4*)(cb + cg);
; #pragma unroll
;             for (int ai = 0; ai < 2; ++ai)
; #pragma unroll
;                 for (int m = 0; m < 4; ++m) {
;                     f32x4 r;
; #pragma unroll
;                     for (int i = 0; i < 4; ++i) {
;                         const float xv = acc[ai][0][m][n][i], xg = acc[ai][1][m][n][i];
;                         const float uv = m > 0 ? acc[ai][0][m > 0 ? m - 1 : 0][n][i] : 0.f, ug = m > 0 ? acc[ai][1][m > 0 ? m - 1 : 0][n][i] : 0.f;
;                         const float dv = m < 3 ? acc[ai][0][m < 3 ? m + 1 : 3][n][i] : 0.f, dg = m < 3 ? acc[ai][1][m < 3 ? m + 1 : 3][n][i] : 0.f;
;                         const float pv = dpp_ror1(fr == 15 ? uv : xv), pg = dpp_ror1(fr == 15 ? ug : xg);
;                         const float nv = dpp_rol1(fr == 0 ? dv : xv), ng = dpp_rol1(fr == 0 ? dg : xg);
;                         const float yv = wv0[i] * pv + wv1[i] * xv + wv2[i] * nv + bv[i];
;                         const float yg = wg0[i] * pg + wg1[i] * xg + wg2[i] * ng + bg[i];
;                         r[i] = yg * sigmoidf_(yg) * yv;
;                     }
;                     st_bf4(ACT + (size_t)(u.pm * BM + ai * HALF + wr * 64 + m * 16 + fr) * FF + cv, r);
	v_pk_mul_f32 v[184:185], v[40:41], v[184:185]
	v_pk_mul_f32 v[186:187], v[42:43], v[186:187]
	v_pk_mul_f32 v[224:225], v[32:33], v[224:225]
	v_pk_mul_f32 v[226:227], v[34:35], v[226:227]
	v_cvt_pk_bf16_f32 v60, v176, v177
	v_cvt_pk_bf16_f32 v61, v178, v179
	v_cvt_pk_bf16_f32 v52, v180, v181
	v_cvt_pk_bf16_f32 v53, v182, v183
	v_cvt_pk_bf16_f32 v44, v184, v185
	v_cvt_pk_bf16_f32 v45, v186, v187
	v_cvt_pk_bf16_f32 v36, v224, v225
	v_cvt_pk_bf16_f32 v37, v226, v227
	global_store_dwordx2 v173, v[60:61], s[0:1] offset:32
	v_add_u32_e32 v175, 0x2c00, v173
	global_store_dwordx2 v175, v[52:53], s[0:1] offset:32
	v_add_u32_e32 v175, 0x5800, v173
	global_store_dwordx2 v175, v[44:45], s[0:1] offset:32
	v_add_u32_e32 v175, 0x8400, v173
	global_store_dwordx2 v175, v[36:37], s[0:1] offset:32
	v_mov_b32_dpp v216, v0 row_shr:1 row_mask:0xf bank_mask:0xf bound_ctrl:1
	v_mov_b32_dpp v217, v1 row_shr:1 row_mask:0xf bank_mask:0xf bound_ctrl:1
	v_mov_b32_dpp v218, v2 row_shr:1 row_mask:0xf bank_mask:0xf bound_ctrl:1
	v_mov_b32_dpp v219, v3 row_shr:1 row_mask:0xf bank_mask:0xf bound_ctrl:1
	v_mov_b32_dpp v220, v24 row_shl:1 row_mask:0xf bank_mask:0xf bound_ctrl:1
	v_mov_b32_dpp v221, v25 row_shl:1 row_mask:0xf bank_mask:0xf bound_ctrl:1
	v_mov_b32_dpp v222, v26 row_shl:1 row_mask:0xf bank_mask:0xf bound_ctrl:1
	v_mov_b32_dpp v223, v27 row_shl:1 row_mask:0xf bank_mask:0xf bound_ctrl:1
	v_pk_mul_f32 v[176:177], v[24:25], v[250:251]
	v_pk_mul_f32 v[178:179], v[26:27], v[252:253]
	v_pk_mul_f32 v[180:181], v[16:17], v[250:251]
	v_pk_mul_f32 v[182:183], v[18:19], v[252:253]
	v_pk_mul_f32 v[184:185], v[8:9], v[250:251]
	v_pk_mul_f32 v[186:187], v[10:11], v[252:253]
	v_pk_mul_f32 v[224:225], v[0:1], v[250:251]
	v_pk_mul_f32 v[226:227], v[2:3], v[252:253]
	v_pk_fma_f32 v[176:177], v[246:247], v[216:217], v[176:177]
	v_pk_fma_f32 v[178:179], v[248:249], v[218:219], v[178:179]
	v_pk_fma_f32 v[180:181], v[246:247], v[24:25], v[180:181]
	v_pk_fma_f32 v[182:183], v[248:249], v[26:27], v[182:183]
	v_pk_fma_f32 v[184:185], v[246:247], v[16:17], v[184:185]
	v_pk_fma_f32 v[186:187], v[248:249], v[18:19], v[186:187]
	v_pk_fma_f32 v[224:225], v[246:247], v[8:9], v[224:225]
	v_pk_fma_f32 v[226:227], v[248:249], v[10:11], v[226:227]
	v_pk_fma_f32 v[176:177], v[208:209], v[16:17], v[176:177]
	v_pk_fma_f32 v[178:179], v[210:211], v[18:19], v[178:179]
	v_pk_fma_f32 v[180:181], v[208:209], v[8:9], v[180:181]
	v_pk_fma_f32 v[182:183], v[210:211], v[10:11], v[182:183]
	v_pk_fma_f32 v[184:185], v[208:209], v[0:1], v[184:185]
	v_pk_fma_f32 v[186:187], v[210:211], v[2:3], v[186:187]
	v_pk_fma_f32 v[224:225], v[208:209], v[220:221], v[224:225]
	v_pk_fma_f32 v[226:227], v[210:211], v[222:223], v[226:227]
	v_pk_add_f32 v[176:177], v[212:213], v[176:177]
	v_pk_add_f32 v[178:179], v[214:215], v[178:179]
	v_pk_add_f32 v[180:181], v[212:213], v[180:181]
	v_pk_add_f32 v[182:183], v[214:215], v[182:183]
	v_pk_add_f32 v[184:185], v[212:213], v[184:185]
	v_pk_add_f32 v[186:187], v[214:215], v[186:187]
	v_pk_add_f32 v[224:225], v[212:213], v[224:225]
	v_pk_add_f32 v[226:227], v[214:215], v[226:227]
	v_mov_b32_dpp v216, v4 row_shr:1 row_mask:0xf bank_mask:0xf bound_ctrl:1
	v_mov_b32_dpp v217, v5 row_shr:1 row_mask:0xf bank_mask:0xf bound_ctrl:1
	v_mov_b32_dpp v218, v6 row_shr:1 row_mask:0xf bank_mask:0xf bound_ctrl:1
	v_mov_b32_dpp v219, v7 row_shr:1 row_mask:0xf bank_mask:0xf bound_ctrl:1
	v_mov_b32_dpp v220, v28 row_shl:1 row_mask:0xf bank_mask:0xf bound_ctrl:1
	v_mov_b32_dpp v221, v29 row_shl:1 row_mask:0xf bank_mask:0xf bound_ctrl:1
	v_mov_b32_dpp v222, v30 row_shl:1 row_mask:0xf bank_mask:0xf bound_ctrl:1
	v_mov_b32_dpp v223, v31 row_shl:1 row_mask:0xf bank_mask:0xf bound_ctrl:1
	v_pk_mul_f32 v[24:25], v[28:29], v[234:235]
	v_pk_mul_f32 v[26:27], v[30:31], v[236:237]
	v_pk_mul_f32 v[16:17], v[20:21], v[234:235]
	v_pk_mul_f32 v[18:19], v[22:23], v[236:237]
	v_pk_mul_f32 v[8:9], v[12:13], v[234:235]
	v_pk_mul_f32 v[10:11], v[14:15], v[236:237]
	v_pk_mul_f32 v[0:1], v[4:5], v[234:235]
	v_pk_mul_f32 v[2:3], v[6:7], v[236:237]
	v_pk_fma_f32 v[24:25], v[230:231], v[216:217], v[24:25]
	v_pk_fma_f32 v[26:27], v[232:233], v[218:219], v[26:27]
	v_pk_fma_f32 v[16:17], v[230:231], v[28:29], v[16:17]
	v_pk_fma_f32 v[18:19], v[232:233], v[30:31], v[18:19]
; __device__ __forceinline__ void st_bf4(bf16_t* p, f32x4 v) { u32x2 w; w.x = pk2(v[0], v[1]); w.y = pk2(v[2], v[3]); *(u32x2*)p = w; }
; __device__ __forceinline__ float sigmoidf_(float x) { return __builtin_amdgcn_rcpf(1.f + __expf(-x)); }
; __device__ __forceinline__ float dpp_ror1(float v) { return __int_as_float(__builtin_amdgcn_update_dpp(0, __float_as_int(v), 0x121, 0xf, 0xf, false)); }
; __device__ __forceinline__ float dpp_rol1(float v) { return __int_as_float(__builtin_amdgcn_update_dpp(0, __float_as_int(v), 0x12F, 0xf, 0xf, false)); }
;     __device__ __forceinline__ void tile(const f32x4 (&acc)[2][2][4][2], const Unit& u, int wr, int wc, int fr, int fq) const {
;     ...
;             const int cv = 128 * u.pn + 32 * wc + 16 * n + 4 * fq, cg = FF + cv;
;             const f32x4 wv0 = *(const f32x4*)(cw + cv), wv1 = *(const f32x4*)(cw + F2 + cv), wv2 = *(const f32x4*)(cw + 2 * F2 + cv), bv = *(const f32x4*)(cb + cv);
;             const f32x4 wg0 = *(const f32x4*)(cw + cg), wg1 = *(const f32x4*)(cw + F2 + cg), wg2 = *(const f32x4*)(cw + 2 * F2 + cg), bg = *(const f32x4*)(cb + cg);
; #pragma unroll
;             for (int ai = 0; ai < 2; ++ai)
; #pragma unroll
;                 for (int m = 0; m < 4; ++m) {
;                     f32x4 r;
; #pragma unroll
;                     for (int i = 0; i < 4; ++i) {
;                         const float xv = acc[ai][0][m][n][i], xg = acc[ai][1][m][n][i];
;                         const float uv = m > 0 ? acc[ai][0][m > 0 ? m - 1 : 0][n][i] : 0.f, ug = m > 0 ? acc[ai][1][m > 0 ? m - 1 : 0][n][i] : 0.f;
;                         const float dv = m < 3 ? acc[ai][0][m < 3 ? m + 1 : 3][n][i] : 0.f, dg = m < 3 ? acc[ai][1][m < 3 ? m + 1 : 3][n][i] : 0.f;
;                         const float pv = dpp_ror1(fr == 15 ? uv : xv), pg = dpp_ror1(fr == 15 ? ug : xg);
;                         const float nv = dpp_rol1(fr == 0 ? dv : xv), ng = dpp_rol1(fr == 0 ? dg : xg);
;                         const float yv = wv0[i] * pv + wv1[i] * xv + wv2[i] * nv + bv[i];
;                         const float yg = wg0[i] * pg + wg1[i] * xg + wg2[i] * ng + bg[i];
;                         r[i] = yg * sigmoidf_(yg) * yv;
;                     }
;                     st_bf4(ACT + (size_t)(u.pm * BM + ai * HALF + wr * 64 + m * 16 + fr) * FF + cv, r);
	v_pk_fma_f32 v[8:9], v[230:231], v[20:21], v[8:9]
	v_pk_fma_f32 v[10:11], v[232:233], v[22:23], v[10:11]
	v_pk_fma_f32 v[0:1], v[230:231], v[12:13], v[0:1]
	v_pk_fma_f32 v[2:3], v[232:233], v[14:15], v[2:3]
	v_pk_fma_f32 v[24:25], v[238:239], v[20:21], v[24:25]
	v_pk_fma_f32 v[26:27], v[240:241], v[22:23], v[26:27]
	v_pk_fma_f32 v[16:17], v[238:239], v[12:13], v[16:17]
	v_pk_fma_f32 v[18:19], v[240:241], v[14:15], v[18:19]
	v_pk_fma_f32 v[8:9], v[238:239], v[4:5], v[8:9]
	v_pk_fma_f32 v[10:11], v[240:241], v[6:7], v[10:11]
	v_pk_fma_f32 v[0:1], v[238:239], v[220:221], v[0:1]
	v_pk_fma_f32 v[2:3], v[240:241], v[222:223], v[2:3]
	v_pk_add_f32 v[24:25], v[242:243], v[24:25]
	v_pk_add_f32 v[26:27], v[244:245], v[26:27]
	v_pk_add_f32 v[16:17], v[242:243], v[16:17]
	v_pk_add_f32 v[18:19], v[244:245], v[18:19]
	v_pk_add_f32 v[8:9], v[242:243], v[8:9]
	v_pk_add_f32 v[10:11], v[244:245], v[10:11]
	v_pk_add_f32 v[0:1], v[242:243], v[0:1]
	v_pk_add_f32 v[2:3], v[244:245], v[2:3]
	v_mul_f32_e32 v28, 0xbfb8aa3b, v176
	v_mul_f32_e32 v29, 0xbfb8aa3b, v177
	v_mul_f32_e32 v30, 0xbfb8aa3b, v178
	v_mul_f32_e32 v31, 0xbfb8aa3b, v179
	v_mul_f32_e32 v20, 0xbfb8aa3b, v180
	v_mul_f32_e32 v21, 0xbfb8aa3b, v181
	v_mul_f32_e32 v22, 0xbfb8aa3b, v182
	v_mul_f32_e32 v23, 0xbfb8aa3b, v183
	v_mul_f32_e32 v12, 0xbfb8aa3b, v184
	v_mul_f32_e32 v13, 0xbfb8aa3b, v185
	v_mul_f32_e32 v14, 0xbfb8aa3b, v186
	v_mul_f32_e32 v15, 0xbfb8aa3b, v187
	v_mul_f32_e32 v4, 0xbfb8aa3b, v224
	v_mul_f32_e32 v5, 0xbfb8aa3b, v225
	v_mul_f32_e32 v6, 0xbfb8aa3b, v226
	v_mul_f32_e32 v7, 0xbfb8aa3b, v227
	v_exp_f32_e32 v28, v28
	v_exp_f32_e32 v29, v29
	v_exp_f32_e32 v30, v30
	v_exp_f32_e32 v31, v31
	v_exp_f32_e32 v20, v20
	v_exp_f32_e32 v21, v21
	v_exp_f32_e32 v22, v22
	v_exp_f32_e32 v23, v23
	v_exp_f32_e32 v12, v12
	v_exp_f32_e32 v13, v13
	v_exp_f32_e32 v14, v14
	v_exp_f32_e32 v15, v15
	v_exp_f32_e32 v4, v4
	v_exp_f32_e32 v5, v5
	v_exp_f32_e32 v6, v6
	v_exp_f32_e32 v7, v7
	v_add_f32_e32 v28, 1.0, v28
	v_add_f32_e32 v29, 1.0, v29
	v_add_f32_e32 v30, 1.0, v30
	v_add_f32_e32 v31, 1.0, v31
	v_add_f32_e32 v20, 1.0, v20
	v_add_f32_e32 v21, 1.0, v21
	v_add_f32_e32 v22, 1.0, v22
	v_add_f32_e32 v23, 1.0, v23
	v_add_f32_e32 v12, 1.0, v12
	v_add_f32_e32 v13, 1.0, v13
	v_add_f32_e32 v14, 1.0, v14
	v_add_f32_e32 v15, 1.0, v15
	v_add_f32_e32 v4, 1.0, v4
	v_add_f32_e32 v5, 1.0, v5
	v_add_f32_e32 v6, 1.0, v6
	v_add_f32_e32 v7, 1.0, v7
	v_rcp_f32_e32 v28, v28
	v_rcp_f32_e32 v29, v29
	v_rcp_f32_e32 v30, v30
	v_rcp_f32_e32 v31, v31
	v_rcp_f32_e32 v20, v20
	v_rcp_f32_e32 v21, v21
	v_rcp_f32_e32 v22, v22
	v_rcp_f32_e32 v23, v23
	v_rcp_f32_e32 v12, v12
	v_rcp_f32_e32 v13, v13
	v_rcp_f32_e32 v14, v14
	v_rcp_f32_e32 v15, v15
	v_rcp_f32_e32 v4, v4
	v_rcp_f32_e32 v5, v5
	v_rcp_f32_e32 v6, v6
	v_rcp_f32_e32 v7, v7
	v_pk_mul_f32 v[176:177], v[176:177], v[28:29]
	v_pk_mul_f32 v[178:179], v[178:179], v[30:31]
	v_pk_mul_f32 v[180:181], v[180:181], v[20:21]
	v_pk_mul_f32 v[182:183], v[182:183], v[22:23]
	v_pk_mul_f32 v[184:185], v[184:185], v[12:13]
	v_pk_mul_f32 v[186:187], v[186:187], v[14:15]
	v_pk_mul_f32 v[224:225], v[224:225], v[4:5]
	v_pk_mul_f32 v[226:227], v[226:227], v[6:7]
	v_pk_mul_f32 v[176:177], v[24:25], v[176:177]
	v_pk_mul_f32 v[178:179], v[26:27], v[178:179]
	v_pk_mul_f32 v[180:181], v[16:17], v[180:181]
	v_pk_mul_f32 v[182:183], v[18:19], v[182:183]
	v_pk_mul_f32 v[184:185], v[8:9], v[184:185]
	v_pk_mul_f32 v[186:187], v[10:11], v[186:187]
	v_pk_mul_f32 v[224:225], v[0:1], v[224:225]
	v_pk_mul_f32 v[226:227], v[2:3], v[226:227]
	v_cvt_pk_bf16_f32 v28, v176, v177
	v_cvt_pk_bf16_f32 v29, v178, v179
	v_cvt_pk_bf16_f32 v20, v180, v181
	v_cvt_pk_bf16_f32 v21, v182, v183
	v_cvt_pk_bf16_f32 v12, v184, v185
	v_cvt_pk_bf16_f32 v13, v186, v187
	v_cvt_pk_bf16_f32 v4, v224, v225
	v_cvt_pk_bf16_f32 v5, v226, v227
	global_store_dwordx2 v174, v[28:29], s[0:1] offset:32
	v_add_u32_e32 v175, 0x2c00, v174
	global_store_dwordx2 v175, v[20:21], s[0:1] offset:32
	v_add_u32_e32 v175, 0x5800, v174
	global_store_dwordx2 v175, v[12:13], s[0:1] offset:32
	v_add_u32_e32 v175, 0x8400, v174
	global_store_dwordx2 v175, v[4:5], s[0:1] offset:32
	s_andn2_b64 vcc, exec, s[20:21]
	s_mov_b64 s[20:21], -1
	s_cbranch_vccnz .LBB0_1795
	s_andn2_b64 vcc, exec, s[2:3]
	s_cbranch_vccnz .LBB0_1794
	s_barrier
	s_branch .LBB0_1794
